# plus qk_prep 16-lane sum-of-squares reductions via DPP instead of ds_bpermute round trips
# baseline (speedup 1.0000x reference)
; __device__ __forceinline__ float xshfl(float v, int o, int lane) { return __int_as_float(__builtin_amdgcn_ds_bpermute((lane ^ o) << 2, __float_as_int(v))); }
; __device__ __forceinline__ unsigned pk2(float lo, float hi) { unsigned r; asm volatile("v_cvt_pk_bf16_f32 %0, %1, %2" : "=v"(r) : "v"(lo), "v"(hi)); return r; }
; __device__ __forceinline__ void qk_prep(bf16_t* H, bf16_t* KC, bf16_t* VC, const float* __restrict__ qg, const float* __restrict__ kg, int gw, int NGW, int lane) {
;     ...
;     for (int t0 = gw; t0 < SEQ; t0 += 4 * NGW) {
;       u32x4 wq[4][3];
; #pragma unroll
;       for (int kk = 0; kk < 4; ++kk)
; #pragma unroll
;         for (int k = 0; k < 3; ++k) wq[kk][k] = ((const u32x4*)(H + (size_t)(t0 + kk * NGW) * DIN + 3072))[lane + 64 * k];
; #pragma unroll
;       for (int kk = 0; kk < 4; ++kk) {
;         const int t = t0 + kk * NGW;
;         u32x4* src = (u32x4*)(H + (size_t)t * DIN + 3072);
;         const float pos = (float)(half ? (t & 63) : (t >> 6));
;         u32x4 w[3];
; #pragma unroll
;         for (int k = 0; k < 3; ++k) w[k] = wq[kk][k];
; #pragma unroll
;         for (int k = 0; k < 3; ++k) {
;             float x[8];
; #pragma unroll
;             for (int e = 0; e < 4; ++e) { x[2 * e] = __uint_as_float(w[k][e] << 16); x[2 * e + 1] = __uint_as_float(w[k][e] & 0xffff0000u); }
;             float ss = 0.f;
; #pragma unroll
;             for (int e = 0; e < 8; ++e) ss += x[e] * x[e];
;             ss += pg8::xshfl(ss, 1, lane); ss += pg8::xshfl(ss, 2, lane); ss += pg8::xshfl(ss, 4, lane); ss += pg8::xshfl(ss, 8, lane);
;             const float rstd = 1.f / sqrtf(ss * (1.f / 128.f) + RMS_EPS);
;             const float* g = (k < 2 ? qg : kg) + 8 * q16;
;             float o[8];
; #pragma unroll
;             for (int e = 0; e < 8; ++e) { const float y = x[e] * rstd * g[e], yp = pg8::xshfl(y, 4, lane); const float ang = pos * invf[e], cs = __cosf(ang), sn = __sinf(ang);
;                 o[e] = first ? y * cs - yp * sn : y * cs + yp * sn; if (k < 2) o[e] *= (att::SCALE * 1.4426950408889634f); }
;             u32x4 r; r.x = pk2(o[0], o[1]); r.y = pk2(o[2], o[3]); r.z = pk2(o[4], o[5]); r.w = pk2(o[6], o[7]);
;             if (k < 2) src[lane + 64 * k] = r;
;             else if (lane < 32) *(u32x4*)(KC + ((size_t)(lane >> 4) * SEQ + t) * 128 + 8 * q16) = r;
.LBB0_131:
	s_ashr_i32 s47, s46, 31
	s_mul_i32 s1, s46, 0x2400
	s_mul_hi_i32 s0, s46, 0x2400
	s_add_u32 s1, s36, s1
	s_addc_u32 s0, s37, s0
	s_add_u32 s28, s1, 0x1800
	s_addc_u32 s29, s0, 0
	global_load_dwordx4 v[86:89], v82, s[28:29]
	global_load_dwordx4 v[24:27], v83, s[28:29]
	global_load_dwordx4 v[52:55], v84, s[28:29]
	s_add_i32 s18, s24, s46
	s_ashr_i32 s19, s18, 31
	s_mul_i32 s1, s18, 0x2400
	s_mul_hi_i32 s0, s18, 0x2400
	s_add_u32 s1, s36, s1
	s_addc_u32 s0, s37, s0
	s_add_u32 s22, s1, 0x1800
	s_addc_u32 s23, s0, 0
	s_add_i32 s10, s14, s46
	s_ashr_i32 s11, s10, 31
	s_mul_i32 s1, s10, 0x2400
	s_mul_hi_i32 s0, s10, 0x2400
	s_add_u32 s1, s36, s1
	s_addc_u32 s0, s37, s0
	s_add_u32 s12, s1, 0x1800
	s_addc_u32 s13, s0, 0
	s_mul_i32 s0, s70, 24
	s_add_i32 s6, s0, s46
	s_ashr_i32 s7, s6, 31
	s_mul_i32 s1, s6, 0x2400
	s_mul_hi_i32 s0, s6, 0x2400
	s_add_u32 s1, s36, s1
	s_addc_u32 s0, s37, s0
	s_add_u32 s8, s1, 0x1800
	s_addc_u32 s9, s0, 0
	s_and_b32 s0, s46, 63
	s_ashr_i32 s1, s46, 6
	v_mov_b32_e32 v32, s0
	v_mov_b32_e32 v33, s1
	v_cndmask_b32_e64 v32, v32, v33, s[44:45]
	v_cvt_f32_i32_e32 v32, v32
	global_load_dwordx4 v[48:51], v82, s[22:23]
	global_load_dwordx4 v[44:47], v83, s[22:23]
	global_load_dwordx4 v[40:43], v84, s[22:23]
	global_load_dwordx4 v[36:39], v82, s[12:13]
	global_load_dwordx4 v[28:31], v83, s[12:13]
	global_load_dwordx4 v[20:23], v84, s[12:13]
	global_load_dwordx4 v[16:19], v82, s[8:9]
	global_load_dwordx4 v[12:15], v83, s[8:9]
	global_load_dwordx4 v[8:11], v84, s[8:9]
	s_waitcnt vmcnt(0)
	v_and_b32_e32 v58, 0xffff0000, v86
	v_lshlrev_b32_e32 v57, 16, v86
	v_mul_f32_e32 v35, v58, v58
	v_lshlrev_b32_e32 v60, 16, v87
	v_fmac_f32_e32 v35, v57, v57
	v_and_b32_e32 v61, 0xffff0000, v87
	v_fmac_f32_e32 v35, v60, v60
	v_lshlrev_b32_e32 v62, 16, v88
	v_fmac_f32_e32 v35, v61, v61
	v_and_b32_e32 v56, 0xffff0000, v88
	v_fmac_f32_e32 v35, v62, v62
	v_lshlrev_b32_e32 v34, 16, v89
	v_fmac_f32_e32 v35, v56, v56
	v_and_b32_e32 v33, 0xffff0000, v89
	v_fmac_f32_e32 v35, v34, v34
	v_fmac_f32_e32 v35, v33, v33
	s_nop 1
	v_mov_b32_dpp v85, v35 quad_perm:[1,0,3,2] row_mask:0xf bank_mask:0xf
	s_waitcnt vmcnt(9)
	v_and_b32_e32 v108, 0xffff0000, v52
	v_lshlrev_b32_e32 v107, 16, v53
	v_and_b32_e32 v106, 0xffff0000, v53
	v_lshlrev_b32_e32 v105, 16, v54
	s_waitcnt lgkmcnt(0)
	v_add_f32_e32 v35, v35, v85
	s_nop 1
	v_mov_b32_dpp v85, v35 quad_perm:[2,3,0,1] row_mask:0xf bank_mask:0xf
	v_and_b32_e32 v104, 0xffff0000, v54
	s_waitcnt lgkmcnt(0)
	v_add_f32_e32 v35, v35, v85
	s_nop 1
	v_mov_b32_dpp v85, v35 row_half_mirror row_mask:0xf bank_mask:0xf
	s_waitcnt lgkmcnt(0)
	v_add_f32_e32 v35, v35, v85
	s_nop 1
	v_mov_b32_dpp v85, v35 row_mirror row_mask:0xf bank_mask:0xf
	s_waitcnt lgkmcnt(0)
	v_add_f32_e32 v35, v35, v85
	v_fmamk_f32 v35, v35, 0x3c000000, v231
	v_cmp_gt_f32_e32 vcc, s16, v35
	v_mul_f32_e32 v85, 0x4f800000, v35
	s_nop 0
	v_cndmask_b32_e32 v35, v35, v85, vcc
	v_sqrt_f32_e32 v85, v35
	s_nop 0
	v_add_u32_e32 v86, -1, v85
	v_fma_f32 v87, -v86, v85, v35
	v_cmp_ge_f32_e64 s[4:5], 0, v87
	v_add_u32_e32 v87, 1, v85
	s_nop 0
	v_cndmask_b32_e64 v86, v85, v86, s[4:5]
	v_fma_f32 v85, -v87, v85, v35
	v_cmp_lt_f32_e64 s[4:5], 0, v85
	s_nop 1
	v_cndmask_b32_e64 v85, v86, v87, s[4:5]
	v_mul_f32_e32 v86, 0x37800000, v85
	v_cndmask_b32_e32 v85, v85, v86, vcc
	v_cmp_class_f32_e32 vcc, v35, v233
	s_nop 1
	v_cndmask_b32_e32 v35, v85, v35, vcc
	v_div_scale_f32 v85, s[0:1], v35, v35, 1.0
	v_rcp_f32_e32 v86, v85
	s_nop 0
	v_fma_f32 v87, -v85, v86, 1.0
	v_fmac_f32_e32 v86, v87, v86
	v_div_scale_f32 v87, vcc, 1.0, v35, 1.0
	v_mul_f32_e32 v88, v87, v86
	v_fma_f32 v89, -v85, v88, v87
	v_fmac_f32_e32 v88, v89, v86
	v_fma_f32 v85, -v85, v88, v87
	v_div_fmas_f32 v85, v85, v86, v88
	v_div_fixup_f32 v35, v85, v35, 1.0
	v_mul_f32_e32 v57, v35, v57
	v_mul_f32_e32 v57, v0, v57
	v_mul_f32_e32 v85, v70, v32
	ds_bpermute_b32 v87, v80, v57
	v_mul_f32_e32 v86, 0.15915494, v85
	v_cos_f32_e32 v85, v86
	v_sin_f32_e32 v86, v86
	v_mul_f32_e32 v58, v35, v58
	v_mul_f32_e32 v58, v1, v58
	ds_bpermute_b32 v89, v80, v58
	s_waitcnt lgkmcnt(1)
	v_mul_f32_e32 v87, v86, v87
	v_cndmask_b32_e64 v87, v87, -v87, s[42:43]
	v_fmac_f32_e32 v87, v85, v57
	v_mul_f32_e32 v57, 0x3e0293ee, v87
	v_mul_f32_e32 v87, v71, v32
	v_mul_f32_e32 v88, 0.15915494, v87
	v_cos_f32_e32 v87, v88
	v_sin_f32_e32 v88, v88
	v_mul_f32_e32 v60, v35, v60
	v_mul_f32_e32 v60, v2, v60
	ds_bpermute_b32 v91, v80, v60
	s_waitcnt lgkmcnt(1)
	v_mul_f32_e32 v89, v88, v89
	v_cndmask_b32_e64 v89, v89, -v89, s[42:43]
	v_fmac_f32_e32 v89, v87, v58
	v_mul_f32_e32 v58, 0x3e0293ee, v89
	v_mul_f32_e32 v89, v72, v32
	v_mul_f32_e32 v90, 0.15915494, v89
	v_cos_f32_e32 v89, v90
	v_sin_f32_e32 v90, v90
	v_mul_f32_e32 v61, v35, v61
	v_mul_f32_e32 v61, v3, v61
	ds_bpermute_b32 v93, v80, v61
	s_waitcnt lgkmcnt(1)
	v_mul_f32_e32 v91, v90, v91
	v_cndmask_b32_e64 v91, v91, -v91, s[42:43]
	v_fmac_f32_e32 v91, v89, v60
	v_mul_f32_e32 v60, 0x3e0293ee, v91
	v_mul_f32_e32 v91, v73, v32
	v_mul_f32_e32 v92, 0.15915494, v91
	v_cos_f32_e32 v91, v92
	v_sin_f32_e32 v92, v92
	v_mul_f32_e32 v62, v35, v62
	v_mul_f32_e32 v62, v4, v62
	ds_bpermute_b32 v95, v80, v62
	s_waitcnt lgkmcnt(1)
	v_mul_f32_e32 v93, v92, v93
	v_cndmask_b32_e64 v93, v93, -v93, s[42:43]
	v_fmac_f32_e32 v93, v91, v61
	v_mul_f32_e32 v61, 0x3e0293ee, v93
	v_mul_f32_e32 v93, v74, v32
	v_mul_f32_e32 v94, 0.15915494, v93
	v_cos_f32_e32 v93, v94
	v_sin_f32_e32 v94, v94
	v_mul_f32_e32 v56, v35, v56
	v_mul_f32_e32 v56, v5, v56
	ds_bpermute_b32 v96, v80, v56
	s_waitcnt lgkmcnt(1)
; __device__ __forceinline__ float xshfl(float v, int o, int lane) { return __int_as_float(__builtin_amdgcn_ds_bpermute((lane ^ o) << 2, __float_as_int(v))); }
; __device__ __forceinline__ unsigned pk2(float lo, float hi) { unsigned r; asm volatile("v_cvt_pk_bf16_f32 %0, %1, %2" : "=v"(r) : "v"(lo), "v"(hi)); return r; }
; __device__ __forceinline__ void qk_prep(bf16_t* H, bf16_t* KC, bf16_t* VC, const float* __restrict__ qg, const float* __restrict__ kg, int gw, int NGW, int lane) {
;     ...
;         for (int k = 0; k < 3; ++k) {
;             float x[8];
; #pragma unroll
;             for (int e = 0; e < 4; ++e) { x[2 * e] = __uint_as_float(w[k][e] << 16); x[2 * e + 1] = __uint_as_float(w[k][e] & 0xffff0000u); }
;             float ss = 0.f;
; #pragma unroll
;             for (int e = 0; e < 8; ++e) ss += x[e] * x[e];
;             ss += pg8::xshfl(ss, 1, lane); ss += pg8::xshfl(ss, 2, lane); ss += pg8::xshfl(ss, 4, lane); ss += pg8::xshfl(ss, 8, lane);
;             const float rstd = 1.f / sqrtf(ss * (1.f / 128.f) + RMS_EPS);
;             const float* g = (k < 2 ? qg : kg) + 8 * q16;
;             float o[8];
; #pragma unroll
;             for (int e = 0; e < 8; ++e) { const float y = x[e] * rstd * g[e], yp = pg8::xshfl(y, 4, lane); const float ang = pos * invf[e], cs = __cosf(ang), sn = __sinf(ang);
;                 o[e] = first ? y * cs - yp * sn : y * cs + yp * sn; if (k < 2) o[e] *= (att::SCALE * 1.4426950408889634f); }
;             u32x4 r; r.x = pk2(o[0], o[1]); r.y = pk2(o[2], o[3]); r.z = pk2(o[4], o[5]); r.w = pk2(o[6], o[7]);
;             if (k < 2) src[lane + 64 * k] = r;
;             else if (lane < 32) *(u32x4*)(KC + ((size_t)(lane >> 4) * SEQ + t) * 128 + 8 * q16) = r;
;             else *(u32x4*)(VC + ((size_t)((lane - 32) >> 4) * SEQ + t) * 128 + 8 * q16) = w[2];
	v_mul_f32_e32 v95, v94, v95
	v_cndmask_b32_e64 v95, v95, -v95, s[42:43]
	v_fmac_f32_e32 v95, v93, v62
	v_mul_f32_e32 v62, 0x3e0293ee, v95
	v_mul_f32_e32 v95, v75, v32
	v_mul_f32_e32 v97, 0.15915494, v95
	v_cos_f32_e32 v95, v97
	v_sin_f32_e32 v97, v97
	v_mul_f32_e32 v34, v35, v34
	v_mul_f32_e32 v34, v6, v34
	ds_bpermute_b32 v99, v80, v34
	s_waitcnt lgkmcnt(1)
	v_mul_f32_e32 v96, v97, v96
	v_cndmask_b32_e64 v96, v96, -v96, s[42:43]
	v_fmac_f32_e32 v96, v95, v56
	v_mul_f32_e32 v56, 0x3e0293ee, v96
	v_mul_f32_e32 v96, v76, v32
	v_mul_f32_e32 v98, 0.15915494, v96
	v_cos_f32_e32 v96, v98
	v_sin_f32_e32 v98, v98
	v_mul_f32_e32 v33, v35, v33
	v_mul_f32_e32 v33, v7, v33
	v_mul_f32_e32 v32, v77, v32
	s_waitcnt lgkmcnt(0)
	v_mul_f32_e32 v99, v98, v99
	v_cndmask_b32_e64 v99, v99, -v99, s[42:43]
	v_fmac_f32_e32 v99, v96, v34
	ds_bpermute_b32 v34, v80, v33
	v_mul_f32_e32 v32, 0.15915494, v32
	v_sin_f32_e32 v100, v32
	v_mul_f32_e32 v101, 0x3e0293ee, v99
	v_cos_f32_e32 v99, v32
	s_waitcnt lgkmcnt(0)
	v_mul_f32_e32 v32, v100, v34
	v_cndmask_b32_e64 v32, v32, -v32, s[42:43]
	v_fmac_f32_e32 v32, v99, v33
	v_mul_f32_e32 v35, 0x3e0293ee, v32
	v_cvt_pk_bf16_f32 v32, v57, v58
	v_cvt_pk_bf16_f32 v33, v60, v61
	v_cvt_pk_bf16_f32 v34, v62, v56
	v_cvt_pk_bf16_f32 v35, v101, v35
	global_store_dwordx4 v82, v[32:35], s[28:29]
	v_lshlrev_b32_e32 v60, 16, v26
	v_and_b32_e32 v61, 0xffff0000, v26
	v_and_b32_e32 v33, 0xffff0000, v24
	v_lshlrev_b32_e32 v32, 16, v24
	v_mul_f32_e32 v26, v33, v33
	v_lshlrev_b32_e32 v34, 16, v25
	v_fmac_f32_e32 v26, v32, v32
	v_and_b32_e32 v35, 0xffff0000, v25
	v_fmac_f32_e32 v26, v34, v34
	v_fmac_f32_e32 v26, v35, v35
	v_fmac_f32_e32 v26, v60, v60
	v_lshlrev_b32_e32 v25, 16, v27
	v_fmac_f32_e32 v26, v61, v61
	v_and_b32_e32 v24, 0xffff0000, v27
	v_fmac_f32_e32 v26, v25, v25
	v_fmac_f32_e32 v26, v24, v24
	s_nop 1
	v_mov_b32_dpp v27, v26 quad_perm:[1,0,3,2] row_mask:0xf bank_mask:0xf
	s_waitcnt lgkmcnt(0)
	v_add_f32_e32 v26, v26, v27
	s_nop 1
	v_mov_b32_dpp v27, v26 quad_perm:[2,3,0,1] row_mask:0xf bank_mask:0xf
	s_waitcnt lgkmcnt(0)
	v_add_f32_e32 v26, v26, v27
	s_nop 1
	v_mov_b32_dpp v27, v26 row_half_mirror row_mask:0xf bank_mask:0xf
	s_waitcnt lgkmcnt(0)
	v_add_f32_e32 v26, v26, v27
	s_nop 1
	v_mov_b32_dpp v27, v26 row_mirror row_mask:0xf bank_mask:0xf
	s_waitcnt lgkmcnt(0)
	v_add_f32_e32 v26, v26, v27
	v_fmamk_f32 v26, v26, 0x3c000000, v231
	v_cmp_gt_f32_e32 vcc, s16, v26
	v_mul_f32_e32 v27, 0x4f800000, v26
	s_nop 0
	v_cndmask_b32_e32 v26, v26, v27, vcc
	v_sqrt_f32_e32 v27, v26
	s_nop 0
	v_add_u32_e32 v56, -1, v27
	v_fma_f32 v57, -v56, v27, v26
	v_cmp_ge_f32_e64 s[4:5], 0, v57
	v_add_u32_e32 v57, 1, v27
	s_nop 0
	v_cndmask_b32_e64 v56, v27, v56, s[4:5]
	v_fma_f32 v27, -v57, v27, v26
	v_cmp_lt_f32_e64 s[4:5], 0, v27
	s_nop 1
	v_cndmask_b32_e64 v27, v56, v57, s[4:5]
	v_mul_f32_e32 v56, 0x37800000, v27
	v_cndmask_b32_e32 v27, v27, v56, vcc
	v_cmp_class_f32_e32 vcc, v26, v233
	s_nop 1
	v_cndmask_b32_e32 v26, v27, v26, vcc
	v_div_scale_f32 v27, s[0:1], v26, v26, 1.0
	v_rcp_f32_e32 v56, v27
	s_nop 0
	v_fma_f32 v57, -v27, v56, 1.0
	v_fmac_f32_e32 v56, v57, v56
	v_div_scale_f32 v57, vcc, 1.0, v26, 1.0
	v_mul_f32_e32 v58, v57, v56
	v_fma_f32 v62, -v27, v58, v57
	v_fmac_f32_e32 v58, v62, v56
	v_fma_f32 v27, -v27, v58, v57
	v_div_fmas_f32 v27, v27, v56, v58
	global_load_dwordx3 v[56:58], v[64:65], off
	v_div_fixup_f32 v26, v27, v26, 1.0
	v_mul_f32_e32 v27, v26, v32
	v_mul_f32_e32 v101, v26, v61
	v_mul_f32_e32 v25, v26, v25
	v_mul_f32_e32 v24, v26, v24
	s_waitcnt vmcnt(0)
	v_mul_f32_e32 v27, v56, v27
	ds_bpermute_b32 v32, v80, v27
	s_waitcnt lgkmcnt(0)
	v_mul_f32_e32 v32, v86, v32
	v_cndmask_b32_e64 v32, v32, -v32, s[42:43]
	v_fmac_f32_e32 v32, v85, v27
	v_mul_f32_e32 v27, 0x3e0293ee, v32
	v_mul_f32_e32 v32, v26, v33
	v_mul_f32_e32 v32, v57, v32
	ds_bpermute_b32 v33, v80, v32
	s_waitcnt lgkmcnt(0)
	v_mul_f32_e32 v33, v88, v33
	v_cndmask_b32_e64 v33, v33, -v33, s[42:43]
	v_fmac_f32_e32 v33, v87, v32
	v_mul_f32_e32 v32, 0x3e0293ee, v33
	v_mul_f32_e32 v33, v26, v34
	v_mul_f32_e32 v33, v58, v33
	ds_bpermute_b32 v34, v80, v33
	s_waitcnt lgkmcnt(0)
	v_mul_f32_e32 v34, v90, v34
	v_cndmask_b32_e64 v34, v34, -v34, s[42:43]
	v_fmac_f32_e32 v34, v89, v33
	v_mul_f32_e32 v33, 0x3e0293ee, v34
	v_mul_f32_e32 v34, v26, v35
	v_mul_f32_e32 v34, v3, v34
	ds_bpermute_b32 v35, v80, v34
	s_waitcnt lgkmcnt(0)
	v_mul_f32_e32 v35, v92, v35
	v_cndmask_b32_e64 v35, v35, -v35, s[42:43]
	v_fmac_f32_e32 v35, v91, v34
	v_mul_f32_e32 v34, 0x3e0293ee, v35
	v_mul_f32_e32 v35, v26, v60
	v_mul_f32_e32 v35, v4, v35
	ds_bpermute_b32 v60, v80, v35
	s_waitcnt lgkmcnt(0)
	v_mul_f32_e32 v60, v94, v60
	v_cndmask_b32_e64 v60, v60, -v60, s[42:43]
	v_fmac_f32_e32 v60, v93, v35
	v_mul_f32_e32 v35, 0x3e0293ee, v60
	global_load_dwordx3 v[60:62], v[64:65], off offset:20
	s_waitcnt vmcnt(0)
	v_mul_f32_e32 v101, v101, v60
	ds_bpermute_b32 v102, v80, v101
	v_mul_f32_e32 v25, v25, v61
	v_mul_f32_e32 v24, v24, v62
	s_waitcnt lgkmcnt(0)
	v_mul_f32_e32 v102, v97, v102
	v_cndmask_b32_e64 v102, v102, -v102, s[42:43]
	v_fmac_f32_e32 v102, v95, v101
	v_mul_f32_e32 v101, 0x3e0293ee, v102
	ds_bpermute_b32 v102, v80, v25
	s_waitcnt lgkmcnt(0)
	v_mul_f32_e32 v102, v98, v102
	v_cndmask_b32_e64 v102, v102, -v102, s[42:43]
	v_fmac_f32_e32 v102, v96, v25
	ds_bpermute_b32 v25, v80, v24
	v_mul_f32_e32 v102, 0x3e0293ee, v102
	s_waitcnt lgkmcnt(0)
; __device__ __forceinline__ float xshfl(float v, int o, int lane) { return __int_as_float(__builtin_amdgcn_ds_bpermute((lane ^ o) << 2, __float_as_int(v))); }
; __device__ __forceinline__ unsigned pk2(float lo, float hi) { unsigned r; asm volatile("v_cvt_pk_bf16_f32 %0, %1, %2" : "=v"(r) : "v"(lo), "v"(hi)); return r; }
; __device__ __forceinline__ void qk_prep(bf16_t* H, bf16_t* KC, bf16_t* VC, const float* __restrict__ qg, const float* __restrict__ kg, int gw, int NGW, int lane) {
;     ...
;         for (int k = 0; k < 3; ++k) {
;             float x[8];
; #pragma unroll
;             for (int e = 0; e < 4; ++e) { x[2 * e] = __uint_as_float(w[k][e] << 16); x[2 * e + 1] = __uint_as_float(w[k][e] & 0xffff0000u); }
;             float ss = 0.f;
; #pragma unroll
;             for (int e = 0; e < 8; ++e) ss += x[e] * x[e];
;             ss += pg8::xshfl(ss, 1, lane); ss += pg8::xshfl(ss, 2, lane); ss += pg8::xshfl(ss, 4, lane); ss += pg8::xshfl(ss, 8, lane);
;             const float rstd = 1.f / sqrtf(ss * (1.f / 128.f) + RMS_EPS);
;             const float* g = (k < 2 ? qg : kg) + 8 * q16;
;             float o[8];
; #pragma unroll
;             for (int e = 0; e < 8; ++e) { const float y = x[e] * rstd * g[e], yp = pg8::xshfl(y, 4, lane); const float ang = pos * invf[e], cs = __cosf(ang), sn = __sinf(ang);
;                 o[e] = first ? y * cs - yp * sn : y * cs + yp * sn; if (k < 2) o[e] *= (att::SCALE * 1.4426950408889634f); }
;             u32x4 r; r.x = pk2(o[0], o[1]); r.y = pk2(o[2], o[3]); r.z = pk2(o[4], o[5]); r.w = pk2(o[6], o[7]);
;             if (k < 2) src[lane + 64 * k] = r;
;             else if (lane < 32) *(u32x4*)(KC + ((size_t)(lane >> 4) * SEQ + t) * 128 + 8 * q16) = r;
;             else *(u32x4*)(VC + ((size_t)((lane - 32) >> 4) * SEQ + t) * 128 + 8 * q16) = w[2];
	v_mul_f32_e32 v25, v100, v25
	v_cndmask_b32_e64 v25, v25, -v25, s[42:43]
	v_fmac_f32_e32 v25, v99, v24
	v_mul_f32_e32 v103, 0x3e0293ee, v25
	v_cvt_pk_bf16_f32 v24, v27, v32
	v_cvt_pk_bf16_f32 v25, v33, v34
	v_cvt_pk_bf16_f32 v26, v35, v101
	v_cvt_pk_bf16_f32 v27, v102, v103
	global_store_dwordx4 v83, v[24:27], s[28:29]
	v_lshlrev_b32_e32 v102, 16, v55
	v_and_b32_e32 v101, 0xffff0000, v55
	v_lshlrev_b32_e32 v24, 16, v52
	v_mul_f32_e32 v25, v108, v108
	v_fmac_f32_e32 v25, v24, v24
	v_fmac_f32_e32 v25, v107, v107
	v_fmac_f32_e32 v25, v106, v106
	v_fmac_f32_e32 v25, v105, v105
	v_fmac_f32_e32 v25, v104, v104
	v_fmac_f32_e32 v25, v102, v102
	v_fmac_f32_e32 v25, v101, v101
	s_nop 1
	v_mov_b32_dpp v26, v25 quad_perm:[1,0,3,2] row_mask:0xf bank_mask:0xf
	s_waitcnt lgkmcnt(0)
	v_add_f32_e32 v25, v25, v26
	s_nop 1
	v_mov_b32_dpp v26, v25 quad_perm:[2,3,0,1] row_mask:0xf bank_mask:0xf
	s_waitcnt lgkmcnt(0)
	v_add_f32_e32 v25, v25, v26
	s_nop 1
	v_mov_b32_dpp v26, v25 row_half_mirror row_mask:0xf bank_mask:0xf
	s_waitcnt lgkmcnt(0)
	v_add_f32_e32 v25, v25, v26
	s_nop 1
	v_mov_b32_dpp v26, v25 row_mirror row_mask:0xf bank_mask:0xf
	s_waitcnt lgkmcnt(0)
	v_add_f32_e32 v25, v25, v26
	v_fmamk_f32 v25, v25, 0x3c000000, v231
	v_cmp_gt_f32_e32 vcc, s16, v25
	v_mul_f32_e32 v26, 0x4f800000, v25
	s_nop 0
	v_cndmask_b32_e32 v25, v25, v26, vcc
	v_sqrt_f32_e32 v26, v25
	s_nop 0
	v_add_u32_e32 v27, -1, v26
	v_fma_f32 v32, -v27, v26, v25
	v_cmp_ge_f32_e64 s[4:5], 0, v32
	v_add_u32_e32 v32, 1, v26
	s_nop 0
	v_cndmask_b32_e64 v27, v26, v27, s[4:5]
	v_fma_f32 v26, -v32, v26, v25
	v_cmp_lt_f32_e64 s[4:5], 0, v26
	s_nop 1
	v_cndmask_b32_e64 v26, v27, v32, s[4:5]
	v_mul_f32_e32 v27, 0x37800000, v26
	v_cndmask_b32_e32 v26, v26, v27, vcc
	v_cmp_class_f32_e32 vcc, v25, v233
	s_nop 1
	v_cndmask_b32_e32 v25, v26, v25, vcc
	v_div_scale_f32 v26, s[0:1], v25, v25, 1.0
	v_rcp_f32_e32 v27, v26
	s_and_b32 s0, s18, 63
	s_ashr_i32 s1, s18, 6
	v_fma_f32 v32, -v26, v27, 1.0
	v_fmac_f32_e32 v27, v32, v27
	v_div_scale_f32 v32, vcc, 1.0, v25, 1.0
	v_mul_f32_e32 v33, v32, v27
	v_fma_f32 v34, -v26, v33, v32
	v_fmac_f32_e32 v33, v34, v27
	v_fma_f32 v26, -v26, v33, v32
	v_div_fmas_f32 v26, v26, v27, v33
	v_div_fixup_f32 v103, v26, v25, 1.0
	v_mul_f32_e32 v109, v103, v24
	global_load_dwordx4 v[24:27], v[66:67], off offset:16
	global_load_dwordx4 v[32:35], v[66:67], off
	s_waitcnt vmcnt(0)
	v_mul_f32_e32 v109, v32, v109
	ds_bpermute_b32 v110, v80, v109
	s_waitcnt lgkmcnt(0)
	v_mul_f32_e32 v86, v86, v110
	v_cndmask_b32_e64 v86, v86, -v86, s[42:43]
	v_fmac_f32_e32 v86, v85, v109
	v_mul_f32_e32 v85, v103, v108
	v_mul_f32_e32 v85, v33, v85
	ds_bpermute_b32 v108, v80, v85
	s_waitcnt lgkmcnt(0)
	v_mul_f32_e32 v88, v88, v108
	v_cndmask_b32_e64 v88, v88, -v88, s[42:43]
	v_fmac_f32_e32 v88, v87, v85
	v_mul_f32_e32 v85, v103, v107
	v_mul_f32_e32 v85, v34, v85
	ds_bpermute_b32 v87, v80, v85
	s_waitcnt lgkmcnt(0)
	v_mul_f32_e32 v87, v90, v87
	v_cndmask_b32_e64 v87, v87, -v87, s[42:43]
	v_fmac_f32_e32 v87, v89, v85
	v_mul_f32_e32 v85, v103, v106
	v_mul_f32_e32 v85, v85, v35
	ds_bpermute_b32 v89, v80, v85
	s_waitcnt lgkmcnt(0)
	v_mul_f32_e32 v89, v92, v89
	v_cndmask_b32_e64 v89, v89, -v89, s[42:43]
	v_fmac_f32_e32 v89, v91, v85
	v_mul_f32_e32 v85, v103, v105
	v_mul_f32_e32 v85, v85, v24
	ds_bpermute_b32 v90, v80, v85
	s_waitcnt lgkmcnt(0)
	v_mul_f32_e32 v90, v94, v90
	v_cndmask_b32_e64 v90, v90, -v90, s[42:43]
	v_fmac_f32_e32 v90, v93, v85
	v_mul_f32_e32 v85, v103, v104
	v_mul_f32_e32 v85, v85, v25
	ds_bpermute_b32 v91, v80, v85
	s_waitcnt lgkmcnt(0)
	v_mul_f32_e32 v91, v97, v91
	v_cndmask_b32_e64 v91, v91, -v91, s[42:43]
	v_fmac_f32_e32 v91, v95, v85
	v_mul_f32_e32 v85, v103, v102
	v_mul_f32_e32 v85, v85, v26
	ds_bpermute_b32 v92, v80, v85
	s_waitcnt lgkmcnt(0)
	v_mul_f32_e32 v92, v98, v92
	v_cndmask_b32_e64 v92, v92, -v92, s[42:43]
	v_fmac_f32_e32 v92, v96, v85
	v_mul_f32_e32 v85, v103, v101
	v_mul_f32_e32 v85, v85, v27
	ds_bpermute_b32 v93, v80, v85
	s_waitcnt lgkmcnt(0)
	v_mul_f32_e32 v93, v100, v93
	v_cndmask_b32_e64 v93, v93, -v93, s[42:43]
	v_fmac_f32_e32 v93, v99, v85
	v_cvt_pk_bf16_f32 v85, v86, v88
	v_cvt_pk_bf16_f32 v88, v87, v89
	v_lshl_add_u64 v[86:87], v[112:113], 0, s[46:47]
	v_lshlrev_b64 v[86:87], 8, v[86:87]
	v_cvt_pk_bf16_f32 v89, v90, v91
	v_cvt_pk_bf16_f32 v90, v92, v93
	v_cndmask_b32_e64 v52, v52, v85, s[40:41]
	v_cndmask_b32_e64 v53, v53, v88, s[40:41]
	v_cndmask_b32_e64 v54, v54, v89, s[40:41]
	v_cndmask_b32_e64 v55, v55, v90, s[40:41]
	v_lshl_add_u64 v[86:87], v[68:69], 0, v[86:87]
	global_store_dwordx4 v[86:87], v[52:55], off
	v_lshlrev_b32_e32 v87, 16, v50
	v_and_b32_e32 v92, 0xffff0000, v50
	v_mov_b32_e32 v52, s0
	v_mov_b32_e32 v53, s1
	v_cndmask_b32_e64 v52, v52, v53, s[44:45]
	v_cvt_f32_i32_e32 v85, v52
	v_lshlrev_b32_e32 v52, 16, v48
	v_and_b32_e32 v48, 0xffff0000, v48
	v_mul_f32_e32 v50, v48, v48
	v_lshlrev_b32_e32 v86, 16, v49
	v_fmac_f32_e32 v50, v52, v52
	v_and_b32_e32 v49, 0xffff0000, v49
	v_fmac_f32_e32 v50, v86, v86
	v_fmac_f32_e32 v50, v49, v49
	v_fmac_f32_e32 v50, v87, v87
	v_lshlrev_b32_e32 v91, 16, v51
	v_fmac_f32_e32 v50, v92, v92
	v_and_b32_e32 v90, 0xffff0000, v51
	v_fmac_f32_e32 v50, v91, v91
	v_fmac_f32_e32 v50, v90, v90
	s_nop 1
	v_mov_b32_dpp v51, v50 quad_perm:[1,0,3,2] row_mask:0xf bank_mask:0xf
	s_waitcnt lgkmcnt(0)
	v_add_f32_e32 v50, v50, v51
	s_nop 1
	v_mov_b32_dpp v51, v50 quad_perm:[2,3,0,1] row_mask:0xf bank_mask:0xf
	s_waitcnt lgkmcnt(0)
	v_add_f32_e32 v50, v50, v51
	s_nop 1
	v_mov_b32_dpp v51, v50 row_half_mirror row_mask:0xf bank_mask:0xf
	s_waitcnt lgkmcnt(0)
	v_add_f32_e32 v50, v50, v51
	s_nop 1
	v_mov_b32_dpp v51, v50 row_mirror row_mask:0xf bank_mask:0xf
	s_waitcnt lgkmcnt(0)
; __device__ __forceinline__ float xshfl(float v, int o, int lane) { return __int_as_float(__builtin_amdgcn_ds_bpermute((lane ^ o) << 2, __float_as_int(v))); }
; __device__ __forceinline__ unsigned pk2(float lo, float hi) { unsigned r; asm volatile("v_cvt_pk_bf16_f32 %0, %1, %2" : "=v"(r) : "v"(lo), "v"(hi)); return r; }
; __device__ __forceinline__ void qk_prep(bf16_t* H, bf16_t* KC, bf16_t* VC, const float* __restrict__ qg, const float* __restrict__ kg, int gw, int NGW, int lane) {
;     ...
;         for (int k = 0; k < 3; ++k) {
;             float x[8];
; #pragma unroll
;             for (int e = 0; e < 4; ++e) { x[2 * e] = __uint_as_float(w[k][e] << 16); x[2 * e + 1] = __uint_as_float(w[k][e] & 0xffff0000u); }
;             float ss = 0.f;
; #pragma unroll
;             for (int e = 0; e < 8; ++e) ss += x[e] * x[e];
;             ss += pg8::xshfl(ss, 1, lane); ss += pg8::xshfl(ss, 2, lane); ss += pg8::xshfl(ss, 4, lane); ss += pg8::xshfl(ss, 8, lane);
;             const float rstd = 1.f / sqrtf(ss * (1.f / 128.f) + RMS_EPS);
;             const float* g = (k < 2 ? qg : kg) + 8 * q16;
;             float o[8];
; #pragma unroll
;             for (int e = 0; e < 8; ++e) { const float y = x[e] * rstd * g[e], yp = pg8::xshfl(y, 4, lane); const float ang = pos * invf[e], cs = __cosf(ang), sn = __sinf(ang);
;                 o[e] = first ? y * cs - yp * sn : y * cs + yp * sn; if (k < 2) o[e] *= (att::SCALE * 1.4426950408889634f); }
;             u32x4 r; r.x = pk2(o[0], o[1]); r.y = pk2(o[2], o[3]); r.z = pk2(o[4], o[5]); r.w = pk2(o[6], o[7]);
;             if (k < 2) src[lane + 64 * k] = r;
;             else if (lane < 32) *(u32x4*)(KC + ((size_t)(lane >> 4) * SEQ + t) * 128 + 8 * q16) = r;
;             else *(u32x4*)(VC + ((size_t)((lane - 32) >> 4) * SEQ + t) * 128 + 8 * q16) = w[2];
	v_add_f32_e32 v50, v50, v51
	v_fmamk_f32 v50, v50, 0x3c000000, v231
	v_cmp_gt_f32_e32 vcc, s16, v50
	v_mul_f32_e32 v51, 0x4f800000, v50
	s_nop 0
	v_cndmask_b32_e32 v50, v50, v51, vcc
	v_sqrt_f32_e32 v51, v50
	s_nop 0
	v_add_u32_e32 v53, -1, v51
	v_fma_f32 v54, -v53, v51, v50
	v_cmp_ge_f32_e64 s[4:5], 0, v54
	v_add_u32_e32 v54, 1, v51
	s_nop 0
	v_cndmask_b32_e64 v53, v51, v53, s[4:5]
	v_fma_f32 v51, -v54, v51, v50
	v_cmp_lt_f32_e64 s[4:5], 0, v51
	s_nop 1
	v_cndmask_b32_e64 v51, v53, v54, s[4:5]
	v_mul_f32_e32 v53, 0x37800000, v51
	v_cndmask_b32_e32 v51, v51, v53, vcc
	v_cmp_class_f32_e32 vcc, v50, v233
	s_nop 1
	v_cndmask_b32_e32 v50, v51, v50, vcc
	v_div_scale_f32 v51, s[0:1], v50, v50, 1.0
	v_rcp_f32_e32 v53, v51
	s_nop 0
	v_fma_f32 v54, -v51, v53, 1.0
	v_fmac_f32_e32 v53, v54, v53
	v_div_scale_f32 v54, vcc, 1.0, v50, 1.0
	v_mul_f32_e32 v55, v54, v53
	v_fma_f32 v88, -v51, v55, v54
	v_fmac_f32_e32 v55, v88, v53
	v_fma_f32 v51, -v51, v55, v54
	v_div_fmas_f32 v51, v51, v53, v55
	v_div_fixup_f32 v96, v51, v50, 1.0
	v_mul_f32_e32 v50, v96, v52
	v_mul_f32_e32 v50, v56, v50
	v_mul_f32_e32 v52, v70, v85
	ds_bpermute_b32 v51, v80, v50
	v_mul_f32_e32 v53, 0.15915494, v52
	v_sin_f32_e32 v54, v53
	v_cos_f32_e32 v52, v53
	v_mul_f32_e32 v48, v96, v48
	v_mul_f32_e32 v48, v57, v48
	s_waitcnt lgkmcnt(0)
	v_mul_f32_e32 v51, v54, v51
	v_cndmask_b32_e64 v51, v51, -v51, s[42:43]
	v_fmac_f32_e32 v51, v52, v50
	v_mul_f32_e32 v95, 0x3e0293ee, v51
	v_mul_f32_e32 v51, v71, v85
	ds_bpermute_b32 v50, v80, v48
	v_mul_f32_e32 v51, 0.15915494, v51
	v_sin_f32_e32 v55, v51
	v_cos_f32_e32 v53, v51
	v_mul_f32_e32 v87, v96, v87
	v_mul_f32_e32 v92, v96, v92
	s_waitcnt lgkmcnt(0)
	v_mul_f32_e32 v50, v55, v50
	v_cndmask_b32_e64 v50, v50, -v50, s[42:43]
	v_fmac_f32_e32 v50, v53, v48
	v_mul_f32_e32 v48, v96, v86
	v_mul_f32_e32 v97, 0x3e0293ee, v50
	v_mul_f32_e32 v48, v58, v48
	v_mul_f32_e32 v50, v72, v85
	ds_bpermute_b32 v86, v80, v48
	v_mul_f32_e32 v51, 0.15915494, v50
	v_cos_f32_e32 v50, v51
	v_sin_f32_e32 v51, v51
	v_mul_f32_e32 v91, v96, v91
	v_mul_f32_e32 v102, v61, v91
	v_mul_f32_e32 v91, v76, v85
	s_waitcnt lgkmcnt(0)
	v_mul_f32_e32 v86, v51, v86
	v_cndmask_b32_e64 v86, v86, -v86, s[42:43]
	v_fmac_f32_e32 v86, v50, v48
	v_mul_f32_e32 v98, 0x3e0293ee, v86
	v_mul_f32_e32 v86, v96, v49
	global_load_dwordx2 v[48:49], v[64:65], off offset:12
	ds_bpermute_b32 v103, v80, v102
	v_mul_f32_e32 v90, v96, v90
	v_mul_f32_e32 v96, v62, v90
	s_waitcnt vmcnt(0)
	v_mul_f32_e32 v89, v48, v86
	v_mul_f32_e32 v86, v73, v85
	ds_bpermute_b32 v93, v80, v89
	v_mul_f32_e32 v88, 0.15915494, v86
	v_cos_f32_e32 v86, v88
	v_sin_f32_e32 v88, v88
	s_waitcnt lgkmcnt(0)
	v_mul_f32_e32 v93, v88, v93
	v_cndmask_b32_e64 v93, v93, -v93, s[42:43]
	v_fmac_f32_e32 v93, v86, v89
	v_mul_f32_e32 v99, 0x3e0293ee, v93
	v_mul_f32_e32 v93, v49, v87
	v_mul_f32_e32 v87, v74, v85
	ds_bpermute_b32 v94, v80, v93
	v_mul_f32_e32 v89, 0.15915494, v87
	v_cos_f32_e32 v87, v89
	v_sin_f32_e32 v89, v89
	s_waitcnt lgkmcnt(0)
	v_mul_f32_e32 v94, v89, v94
	v_cndmask_b32_e64 v94, v94, -v94, s[42:43]
	v_fmac_f32_e32 v94, v87, v93
	v_mul_f32_e32 v93, v60, v92
	v_mul_f32_e32 v92, v75, v85
	v_mul_f32_e32 v100, 0x3e0293ee, v94
	ds_bpermute_b32 v101, v80, v93
	v_mul_f32_e32 v94, 0.15915494, v92
	v_cos_f32_e32 v92, v94
	v_sin_f32_e32 v94, v94
	v_mul_f32_e32 v85, v77, v85
	v_mul_f32_e32 v90, 0.15915494, v85
	v_cos_f32_e32 v85, v90
	s_waitcnt lgkmcnt(0)
	v_mul_f32_e32 v101, v94, v101
	v_cndmask_b32_e64 v101, v101, -v101, s[42:43]
	v_fmac_f32_e32 v101, v92, v93
	v_mul_f32_e32 v93, 0.15915494, v91
	v_cos_f32_e32 v91, v93
	v_sin_f32_e32 v93, v93
	v_sin_f32_e32 v90, v90
	v_mul_f32_e32 v101, 0x3e0293ee, v101
	v_mul_f32_e32 v103, v93, v103
	v_cndmask_b32_e64 v103, v103, -v103, s[42:43]
	v_fmac_f32_e32 v103, v91, v102
	v_mul_f32_e32 v102, 0x3e0293ee, v103
	ds_bpermute_b32 v103, v80, v96
	s_waitcnt lgkmcnt(0)
	v_mul_f32_e32 v103, v90, v103
	v_cndmask_b32_e64 v103, v103, -v103, s[42:43]
	v_fmac_f32_e32 v103, v85, v96
	v_mul_f32_e32 v103, 0x3e0293ee, v103
	v_cvt_pk_bf16_f32 v96, v95, v97
	v_cvt_pk_bf16_f32 v97, v98, v99
	v_cvt_pk_bf16_f32 v98, v100, v101
	v_cvt_pk_bf16_f32 v99, v102, v103
	v_lshlrev_b32_e32 v95, 16, v44
	v_and_b32_e32 v44, 0xffff0000, v44
	global_store_dwordx4 v82, v[96:99], s[22:23]
	s_nop 1
	v_mul_f32_e32 v99, v44, v44
	v_lshlrev_b32_e32 v96, 16, v45
	v_fmac_f32_e32 v99, v95, v95
	v_and_b32_e32 v45, 0xffff0000, v45
	v_fmac_f32_e32 v99, v96, v96
	v_lshlrev_b32_e32 v97, 16, v46
	v_fmac_f32_e32 v99, v45, v45
	v_and_b32_e32 v46, 0xffff0000, v46
	v_fmac_f32_e32 v99, v97, v97
	v_lshlrev_b32_e32 v98, 16, v47
	v_fmac_f32_e32 v99, v46, v46
	v_and_b32_e32 v47, 0xffff0000, v47
	v_fmac_f32_e32 v99, v98, v98
	v_fmac_f32_e32 v99, v47, v47
	s_nop 1
	v_mov_b32_dpp v100, v99 quad_perm:[1,0,3,2] row_mask:0xf bank_mask:0xf
	s_waitcnt lgkmcnt(0)
	v_add_f32_e32 v99, v99, v100
	s_nop 1
	v_mov_b32_dpp v100, v99 quad_perm:[2,3,0,1] row_mask:0xf bank_mask:0xf
	s_waitcnt lgkmcnt(0)
	v_add_f32_e32 v99, v99, v100
	s_nop 1
	v_mov_b32_dpp v100, v99 row_half_mirror row_mask:0xf bank_mask:0xf
	s_waitcnt lgkmcnt(0)
	v_add_f32_e32 v99, v99, v100
	s_nop 1
	v_mov_b32_dpp v100, v99 row_mirror row_mask:0xf bank_mask:0xf
	s_waitcnt lgkmcnt(0)
; __device__ __forceinline__ float xshfl(float v, int o, int lane) { return __int_as_float(__builtin_amdgcn_ds_bpermute((lane ^ o) << 2, __float_as_int(v))); }
; __device__ __forceinline__ unsigned pk2(float lo, float hi) { unsigned r; asm volatile("v_cvt_pk_bf16_f32 %0, %1, %2" : "=v"(r) : "v"(lo), "v"(hi)); return r; }
; __device__ __forceinline__ void qk_prep(bf16_t* H, bf16_t* KC, bf16_t* VC, const float* __restrict__ qg, const float* __restrict__ kg, int gw, int NGW, int lane) {
;     ...
;         for (int k = 0; k < 3; ++k) {
;             float x[8];
; #pragma unroll
;             for (int e = 0; e < 4; ++e) { x[2 * e] = __uint_as_float(w[k][e] << 16); x[2 * e + 1] = __uint_as_float(w[k][e] & 0xffff0000u); }
;             float ss = 0.f;
; #pragma unroll
;             for (int e = 0; e < 8; ++e) ss += x[e] * x[e];
;             ss += pg8::xshfl(ss, 1, lane); ss += pg8::xshfl(ss, 2, lane); ss += pg8::xshfl(ss, 4, lane); ss += pg8::xshfl(ss, 8, lane);
;             const float rstd = 1.f / sqrtf(ss * (1.f / 128.f) + RMS_EPS);
;             const float* g = (k < 2 ? qg : kg) + 8 * q16;
;             float o[8];
; #pragma unroll
;             for (int e = 0; e < 8; ++e) { const float y = x[e] * rstd * g[e], yp = pg8::xshfl(y, 4, lane); const float ang = pos * invf[e], cs = __cosf(ang), sn = __sinf(ang);
;                 o[e] = first ? y * cs - yp * sn : y * cs + yp * sn; if (k < 2) o[e] *= (att::SCALE * 1.4426950408889634f); }
;             u32x4 r; r.x = pk2(o[0], o[1]); r.y = pk2(o[2], o[3]); r.z = pk2(o[4], o[5]); r.w = pk2(o[6], o[7]);
;             if (k < 2) src[lane + 64 * k] = r;
;             else if (lane < 32) *(u32x4*)(KC + ((size_t)(lane >> 4) * SEQ + t) * 128 + 8 * q16) = r;
;             else *(u32x4*)(VC + ((size_t)((lane - 32) >> 4) * SEQ + t) * 128 + 8 * q16) = w[2];
	v_add_f32_e32 v99, v99, v100
	v_fmamk_f32 v99, v99, 0x3c000000, v231
	v_cmp_gt_f32_e32 vcc, s16, v99
	v_mul_f32_e32 v100, 0x4f800000, v99
	s_nop 0
	v_cndmask_b32_e32 v99, v99, v100, vcc
	v_sqrt_f32_e32 v100, v99
	s_nop 0
	v_add_u32_e32 v101, -1, v100
	v_fma_f32 v102, -v101, v100, v99
	v_cmp_ge_f32_e64 s[4:5], 0, v102
	v_add_u32_e32 v102, 1, v100
	s_nop 0
	v_cndmask_b32_e64 v101, v100, v101, s[4:5]
	v_fma_f32 v100, -v102, v100, v99
	v_cmp_lt_f32_e64 s[4:5], 0, v100
	s_nop 1
	v_cndmask_b32_e64 v100, v101, v102, s[4:5]
	v_mul_f32_e32 v101, 0x37800000, v100
	v_cndmask_b32_e32 v100, v100, v101, vcc
	v_cmp_class_f32_e32 vcc, v99, v233
	s_nop 1
	v_cndmask_b32_e32 v99, v100, v99, vcc
	v_div_scale_f32 v100, s[0:1], v99, v99, 1.0
	v_rcp_f32_e32 v101, v100
	s_nop 0
	v_fma_f32 v102, -v100, v101, 1.0
	v_fmac_f32_e32 v101, v102, v101
	v_div_scale_f32 v102, vcc, 1.0, v99, 1.0
	v_mul_f32_e32 v103, v102, v101
	v_fma_f32 v104, -v100, v103, v102
	v_fmac_f32_e32 v103, v104, v101
	v_fma_f32 v100, -v100, v103, v102
	v_div_fmas_f32 v100, v100, v101, v103
	v_div_fixup_f32 v99, v100, v99, 1.0
	v_mul_f32_e32 v95, v99, v95
	v_mul_f32_e32 v95, v56, v95
	ds_bpermute_b32 v100, v80, v95
	v_mul_f32_e32 v44, v99, v44
	v_mul_f32_e32 v44, v57, v44
	v_mul_f32_e32 v96, v99, v96
	v_mul_f32_e32 v96, v58, v96
	s_waitcnt lgkmcnt(0)
	v_mul_f32_e32 v100, v54, v100
	v_cndmask_b32_e64 v100, v100, -v100, s[42:43]
	v_fmac_f32_e32 v100, v52, v95
	v_mul_f32_e32 v95, 0x3e0293ee, v100
	ds_bpermute_b32 v100, v80, v44
	v_mul_f32_e32 v45, v99, v45
	v_mul_f32_e32 v45, v48, v45
	v_mul_f32_e32 v97, v99, v97
	v_mul_f32_e32 v97, v49, v97
	s_waitcnt lgkmcnt(0)
	v_mul_f32_e32 v100, v55, v100
	v_cndmask_b32_e64 v100, v100, -v100, s[42:43]
	v_fmac_f32_e32 v100, v53, v44
	v_mul_f32_e32 v44, 0x3e0293ee, v100
	ds_bpermute_b32 v100, v80, v96
	v_mul_f32_e32 v46, v99, v46
	v_mul_f32_e32 v46, v60, v46
	v_mul_f32_e32 v47, v99, v47
	v_mul_f32_e32 v98, v99, v98
	s_waitcnt lgkmcnt(0)
	v_mul_f32_e32 v100, v51, v100
	v_cndmask_b32_e64 v100, v100, -v100, s[42:43]
	v_fmac_f32_e32 v100, v50, v96
	v_mul_f32_e32 v96, 0x3e0293ee, v100
	ds_bpermute_b32 v100, v80, v45
	v_mul_f32_e32 v47, v62, v47
	v_mul_f32_e32 v98, v61, v98
	ds_bpermute_b32 v99, v80, v47
	v_cvt_pk_bf16_f32 v44, v95, v44
	s_waitcnt lgkmcnt(1)
	v_mul_f32_e32 v100, v88, v100
	v_cndmask_b32_e64 v100, v100, -v100, s[42:43]
	v_fmac_f32_e32 v100, v86, v45
	v_mul_f32_e32 v45, 0x3e0293ee, v100
	ds_bpermute_b32 v100, v80, v97
	s_waitcnt lgkmcnt(1)
	v_mul_f32_e32 v99, v90, v99
	v_cndmask_b32_e64 v99, v99, -v99, s[42:43]
	v_fmac_f32_e32 v99, v85, v47
	v_mul_f32_e32 v47, 0x3e0293ee, v99
	s_waitcnt lgkmcnt(0)
	v_mul_f32_e32 v100, v89, v100
	v_cndmask_b32_e64 v100, v100, -v100, s[42:43]
	v_fmac_f32_e32 v100, v87, v97
	v_mul_f32_e32 v97, 0x3e0293ee, v100
	ds_bpermute_b32 v100, v80, v46
	v_cvt_pk_bf16_f32 v45, v96, v45
	v_lshlrev_b32_e32 v95, 16, v42
	v_and_b32_e32 v96, 0xffff0000, v42
	s_waitcnt lgkmcnt(0)
	v_mul_f32_e32 v100, v94, v100
	v_cndmask_b32_e64 v100, v100, -v100, s[42:43]
	v_fmac_f32_e32 v100, v92, v46
	v_mul_f32_e32 v46, 0x3e0293ee, v100
	ds_bpermute_b32 v100, v80, v98
	v_cvt_pk_bf16_f32 v46, v97, v46
	v_lshlrev_b32_e32 v97, 16, v43
	s_waitcnt lgkmcnt(0)
	v_mul_f32_e32 v100, v93, v100
	v_cndmask_b32_e64 v100, v100, -v100, s[42:43]
	v_fmac_f32_e32 v100, v91, v98
	v_mul_f32_e32 v98, 0x3e0293ee, v100
	v_cvt_pk_bf16_f32 v47, v98, v47
	global_store_dwordx4 v83, v[44:47], s[22:23]
	v_and_b32_e32 v98, 0xffff0000, v43
	s_nop 0
	v_and_b32_e32 v45, 0xffff0000, v40
	v_lshlrev_b32_e32 v44, 16, v40
	v_mul_f32_e32 v99, v45, v45
	v_lshlrev_b32_e32 v46, 16, v41
	v_fmac_f32_e32 v99, v44, v44
	v_and_b32_e32 v47, 0xffff0000, v41
	v_fmac_f32_e32 v99, v46, v46
	v_fmac_f32_e32 v99, v47, v47
	v_fmac_f32_e32 v99, v95, v95
	v_fmac_f32_e32 v99, v96, v96
	v_fmac_f32_e32 v99, v97, v97
	v_fmac_f32_e32 v99, v98, v98
	s_nop 1
	v_mov_b32_dpp v100, v99 quad_perm:[1,0,3,2] row_mask:0xf bank_mask:0xf
	s_waitcnt lgkmcnt(0)
	v_add_f32_e32 v99, v99, v100
	s_nop 1
	v_mov_b32_dpp v100, v99 quad_perm:[2,3,0,1] row_mask:0xf bank_mask:0xf
	s_waitcnt lgkmcnt(0)
	v_add_f32_e32 v99, v99, v100
	s_nop 1
	v_mov_b32_dpp v100, v99 row_half_mirror row_mask:0xf bank_mask:0xf
	s_waitcnt lgkmcnt(0)
	v_add_f32_e32 v99, v99, v100
	s_nop 1
	v_mov_b32_dpp v100, v99 row_mirror row_mask:0xf bank_mask:0xf
	s_waitcnt lgkmcnt(0)
	v_add_f32_e32 v99, v99, v100
	v_fmamk_f32 v99, v99, 0x3c000000, v231
	v_cmp_gt_f32_e32 vcc, s16, v99
	v_mul_f32_e32 v100, 0x4f800000, v99
	s_nop 0
	v_cndmask_b32_e32 v99, v99, v100, vcc
	v_sqrt_f32_e32 v100, v99
	s_nop 0
	v_add_u32_e32 v101, -1, v100
	v_fma_f32 v102, -v101, v100, v99
	v_cmp_ge_f32_e64 s[4:5], 0, v102
	v_add_u32_e32 v102, 1, v100
	s_nop 0
	v_cndmask_b32_e64 v101, v100, v101, s[4:5]
	v_fma_f32 v100, -v102, v100, v99
	v_cmp_lt_f32_e64 s[4:5], 0, v100
	s_nop 1
	v_cndmask_b32_e64 v100, v101, v102, s[4:5]
	v_mul_f32_e32 v101, 0x37800000, v100
	v_cndmask_b32_e32 v100, v100, v101, vcc
	v_cmp_class_f32_e32 vcc, v99, v233
	s_nop 1
	v_cndmask_b32_e32 v99, v100, v99, vcc
	v_div_scale_f32 v100, s[0:1], v99, v99, 1.0
	v_rcp_f32_e32 v101, v100
	s_add_i32 s0, s24, s18
	s_and_b32 s1, s10, 63
	s_ashr_i32 s4, s0, 6
	v_fma_f32 v102, -v100, v101, 1.0
	v_fmac_f32_e32 v101, v102, v101
	v_div_scale_f32 v102, vcc, 1.0, v99, 1.0
	v_mul_f32_e32 v103, v102, v101
	v_fma_f32 v104, -v100, v103, v102
	v_fmac_f32_e32 v103, v104, v101
	v_fma_f32 v100, -v100, v103, v102
	v_div_fmas_f32 v100, v100, v101, v103
	v_div_fixup_f32 v99, v100, v99, 1.0
	v_mul_f32_e32 v44, v99, v44
	v_mul_f32_e32 v44, v32, v44
	ds_bpermute_b32 v100, v80, v44
	s_add_i32 s0, s24, s0
	s_add_i32 s46, s24, s0
	s_waitcnt lgkmcnt(0)
; __device__ __forceinline__ float xshfl(float v, int o, int lane) { return __int_as_float(__builtin_amdgcn_ds_bpermute((lane ^ o) << 2, __float_as_int(v))); }
; __device__ __forceinline__ unsigned pk2(float lo, float hi) { unsigned r; asm volatile("v_cvt_pk_bf16_f32 %0, %1, %2" : "=v"(r) : "v"(lo), "v"(hi)); return r; }
; __device__ __forceinline__ void qk_prep(bf16_t* H, bf16_t* KC, bf16_t* VC, const float* __restrict__ qg, const float* __restrict__ kg, int gw, int NGW, int lane) {
;     ...
;         for (int k = 0; k < 3; ++k) {
;             float x[8];
; #pragma unroll
;             for (int e = 0; e < 4; ++e) { x[2 * e] = __uint_as_float(w[k][e] << 16); x[2 * e + 1] = __uint_as_float(w[k][e] & 0xffff0000u); }
;             float ss = 0.f;
; #pragma unroll
;             for (int e = 0; e < 8; ++e) ss += x[e] * x[e];
;             ss += pg8::xshfl(ss, 1, lane); ss += pg8::xshfl(ss, 2, lane); ss += pg8::xshfl(ss, 4, lane); ss += pg8::xshfl(ss, 8, lane);
;             const float rstd = 1.f / sqrtf(ss * (1.f / 128.f) + RMS_EPS);
;             const float* g = (k < 2 ? qg : kg) + 8 * q16;
;             float o[8];
; #pragma unroll
;             for (int e = 0; e < 8; ++e) { const float y = x[e] * rstd * g[e], yp = pg8::xshfl(y, 4, lane); const float ang = pos * invf[e], cs = __cosf(ang), sn = __sinf(ang);
;                 o[e] = first ? y * cs - yp * sn : y * cs + yp * sn; if (k < 2) o[e] *= (att::SCALE * 1.4426950408889634f); }
;             u32x4 r; r.x = pk2(o[0], o[1]); r.y = pk2(o[2], o[3]); r.z = pk2(o[4], o[5]); r.w = pk2(o[6], o[7]);
;             if (k < 2) src[lane + 64 * k] = r;
;             else if (lane < 32) *(u32x4*)(KC + ((size_t)(lane >> 4) * SEQ + t) * 128 + 8 * q16) = r;
;             else *(u32x4*)(VC + ((size_t)((lane - 32) >> 4) * SEQ + t) * 128 + 8 * q16) = w[2];
	v_mul_f32_e32 v54, v54, v100
	v_cndmask_b32_e64 v54, v54, -v54, s[42:43]
	v_fmac_f32_e32 v54, v52, v44
	v_mul_f32_e32 v44, v99, v45
	v_mul_f32_e32 v44, v33, v44
	ds_bpermute_b32 v45, v80, v44
	s_waitcnt lgkmcnt(0)
	v_mul_f32_e32 v45, v55, v45
	v_cndmask_b32_e64 v45, v45, -v45, s[42:43]
	v_fmac_f32_e32 v45, v53, v44
	v_mul_f32_e32 v44, v99, v46
	v_mul_f32_e32 v44, v34, v44
	ds_bpermute_b32 v46, v80, v44
	v_cvt_pk_bf16_f32 v54, v54, v45
	s_waitcnt lgkmcnt(0)
	v_mul_f32_e32 v46, v51, v46
	v_cndmask_b32_e64 v46, v46, -v46, s[42:43]
	v_fmac_f32_e32 v46, v50, v44
	v_mul_f32_e32 v44, v99, v47
	v_mul_f32_e32 v44, v35, v44
	ds_bpermute_b32 v47, v80, v44
	v_cndmask_b32_e64 v40, v40, v54, s[40:41]
	v_and_b32_e32 v54, 0xffff0000, v39
	s_waitcnt lgkmcnt(0)
	v_mul_f32_e32 v47, v88, v47
	v_cndmask_b32_e64 v47, v47, -v47, s[42:43]
	v_fmac_f32_e32 v47, v86, v44
	v_mul_f32_e32 v44, v99, v95
	v_mul_f32_e32 v44, v24, v44
	ds_bpermute_b32 v50, v80, v44
	v_cvt_pk_bf16_f32 v46, v46, v47
	s_waitcnt lgkmcnt(0)
	v_mul_f32_e32 v50, v89, v50
	v_cndmask_b32_e64 v50, v50, -v50, s[42:43]
	v_fmac_f32_e32 v50, v87, v44
	v_mul_f32_e32 v44, v99, v96
	v_mul_f32_e32 v44, v25, v44
	ds_bpermute_b32 v51, v80, v44
	v_cndmask_b32_e64 v41, v41, v46, s[40:41]
	s_waitcnt lgkmcnt(0)
	v_mul_f32_e32 v51, v94, v51
	v_cndmask_b32_e64 v51, v51, -v51, s[42:43]
	v_fmac_f32_e32 v51, v92, v44
	v_mul_f32_e32 v44, v99, v97
	v_mul_f32_e32 v44, v26, v44
	ds_bpermute_b32 v52, v80, v44
	v_cvt_pk_bf16_f32 v47, v50, v51
	s_waitcnt lgkmcnt(0)
	v_mul_f32_e32 v52, v93, v52
	v_cndmask_b32_e64 v52, v52, -v52, s[42:43]
	v_fmac_f32_e32 v52, v91, v44
	v_mul_f32_e32 v44, v99, v98
	v_mul_f32_e32 v44, v27, v44
	ds_bpermute_b32 v53, v80, v44
	v_cndmask_b32_e64 v42, v42, v47, s[40:41]
	v_and_b32_e32 v47, 0xffff0000, v38
	s_waitcnt lgkmcnt(0)
	v_mul_f32_e32 v53, v90, v53
	v_cndmask_b32_e64 v53, v53, -v53, s[42:43]
	v_fmac_f32_e32 v53, v85, v44
	v_lshl_add_u64 v[44:45], v[112:113], 0, s[18:19]
	v_lshlrev_b64 v[44:45], 8, v[44:45]
	v_cvt_pk_bf16_f32 v50, v52, v53
	v_lshl_add_u64 v[44:45], v[68:69], 0, v[44:45]
	v_cndmask_b32_e64 v43, v43, v50, s[40:41]
	global_store_dwordx4 v[44:45], v[40:43], off
	v_lshlrev_b32_e32 v45, 16, v38
	v_lshlrev_b32_e32 v50, 16, v39
	v_mov_b32_e32 v40, s1
	v_mov_b32_e32 v41, s4
	v_cndmask_b32_e64 v40, v40, v41, s[44:45]
	v_and_b32_e32 v41, 0xffff0000, v36
	v_cvt_f32_i32_e32 v46, v40
	v_lshlrev_b32_e32 v40, 16, v36
	v_mul_f32_e32 v36, v41, v41
	v_lshlrev_b32_e32 v42, 16, v37
	v_fmac_f32_e32 v36, v40, v40
	v_and_b32_e32 v43, 0xffff0000, v37
	v_fmac_f32_e32 v36, v42, v42
	v_fmac_f32_e32 v36, v43, v43
	v_fmac_f32_e32 v36, v45, v45
	v_fmac_f32_e32 v36, v47, v47
	v_fmac_f32_e32 v36, v50, v50
	v_fmac_f32_e32 v36, v54, v54
	s_nop 1
	v_mov_b32_dpp v37, v36 quad_perm:[1,0,3,2] row_mask:0xf bank_mask:0xf
	s_and_b32 s1, s6, 63
	s_waitcnt lgkmcnt(0)
	v_add_f32_e32 v36, v36, v37
	s_nop 1
	v_mov_b32_dpp v37, v36 quad_perm:[2,3,0,1] row_mask:0xf bank_mask:0xf
	s_waitcnt lgkmcnt(0)
	v_add_f32_e32 v36, v36, v37
	s_nop 1
	v_mov_b32_dpp v37, v36 row_half_mirror row_mask:0xf bank_mask:0xf
	s_waitcnt lgkmcnt(0)
	v_add_f32_e32 v36, v36, v37
	s_nop 1
	v_mov_b32_dpp v37, v36 row_mirror row_mask:0xf bank_mask:0xf
	s_waitcnt lgkmcnt(0)
	v_add_f32_e32 v36, v36, v37
	v_fmamk_f32 v36, v36, 0x3c000000, v231
	v_cmp_gt_f32_e32 vcc, s16, v36
	v_mul_f32_e32 v37, 0x4f800000, v36
	s_nop 0
	v_cndmask_b32_e32 v36, v36, v37, vcc
	v_sqrt_f32_e32 v37, v36
	s_nop 0
	v_add_u32_e32 v38, -1, v37
	v_fma_f32 v39, -v38, v37, v36
	v_cmp_ge_f32_e64 s[4:5], 0, v39
	v_add_u32_e32 v39, 1, v37
	s_nop 0
	v_cndmask_b32_e64 v38, v37, v38, s[4:5]
	v_fma_f32 v37, -v39, v37, v36
	v_cmp_lt_f32_e64 s[4:5], 0, v37
	s_nop 1
	v_cndmask_b32_e64 v37, v38, v39, s[4:5]
	v_mul_f32_e32 v38, 0x37800000, v37
	v_cndmask_b32_e32 v37, v37, v38, vcc
	v_cmp_class_f32_e32 vcc, v36, v233
	s_nop 1
	v_cndmask_b32_e32 v36, v37, v36, vcc
	v_div_scale_f32 v37, s[4:5], v36, v36, 1.0
	v_rcp_f32_e32 v38, v37
	s_nop 0
	v_fma_f32 v39, -v37, v38, 1.0
	v_fmac_f32_e32 v38, v39, v38
	v_div_scale_f32 v39, vcc, 1.0, v36, 1.0
	v_mul_f32_e32 v44, v39, v38
	v_fma_f32 v51, -v37, v44, v39
	v_fmac_f32_e32 v44, v51, v38
	v_fma_f32 v37, -v37, v44, v39
	v_div_fmas_f32 v37, v37, v38, v44
	v_div_fixup_f32 v55, v37, v36, 1.0
	v_mul_f32_e32 v36, v55, v40
	v_mul_f32_e32 v38, v56, v36
	v_mul_f32_e32 v36, v70, v46
	ds_bpermute_b32 v39, v80, v38
	v_mul_f32_e32 v37, 0.15915494, v36
	v_cos_f32_e32 v36, v37
	v_sin_f32_e32 v37, v37
	v_mul_f32_e32 v47, v55, v47
	v_mul_f32_e32 v47, v60, v47
	s_waitcnt lgkmcnt(0)
	v_mul_f32_e32 v39, v37, v39
	v_cndmask_b32_e64 v39, v39, -v39, s[42:43]
	v_fmac_f32_e32 v39, v36, v38
	v_mul_f32_e32 v38, v55, v41
	v_mul_f32_e32 v85, 0x3e0293ee, v39
	v_mul_f32_e32 v39, v57, v38
	v_mul_f32_e32 v38, v71, v46
	ds_bpermute_b32 v41, v80, v39
	v_mul_f32_e32 v40, 0.15915494, v38
	v_cos_f32_e32 v38, v40
	v_sin_f32_e32 v40, v40
	s_waitcnt lgkmcnt(0)
	v_mul_f32_e32 v41, v40, v41
	v_cndmask_b32_e64 v41, v41, -v41, s[42:43]
	v_fmac_f32_e32 v41, v38, v39
	v_mul_f32_e32 v39, v55, v42
	v_mul_f32_e32 v42, v58, v39
	v_mul_f32_e32 v39, v72, v46
	v_mul_f32_e32 v86, 0x3e0293ee, v41
	ds_bpermute_b32 v44, v80, v42
	v_mul_f32_e32 v41, 0.15915494, v39
	v_cos_f32_e32 v39, v41
	v_sin_f32_e32 v41, v41
	v_cvt_pk_bf16_f32 v86, v85, v86
	v_lshlrev_b32_e32 v85, 16, v30
	v_and_b32_e32 v30, 0xffff0000, v30
	s_waitcnt lgkmcnt(0)
	v_mul_f32_e32 v44, v41, v44
	v_cndmask_b32_e64 v44, v44, -v44, s[42:43]
	v_fmac_f32_e32 v44, v39, v42
	v_mul_f32_e32 v42, v55, v43
	v_mul_f32_e32 v43, v48, v42
	v_mul_f32_e32 v42, v73, v46
	v_mul_f32_e32 v87, 0x3e0293ee, v44
	ds_bpermute_b32 v51, v80, v43
	v_mul_f32_e32 v44, 0.15915494, v42
	v_cos_f32_e32 v42, v44
	v_sin_f32_e32 v44, v44
	s_waitcnt lgkmcnt(0)
; __device__ __forceinline__ float xshfl(float v, int o, int lane) { return __int_as_float(__builtin_amdgcn_ds_bpermute((lane ^ o) << 2, __float_as_int(v))); }
; __device__ __forceinline__ unsigned pk2(float lo, float hi) { unsigned r; asm volatile("v_cvt_pk_bf16_f32 %0, %1, %2" : "=v"(r) : "v"(lo), "v"(hi)); return r; }
; __device__ __forceinline__ void qk_prep(bf16_t* H, bf16_t* KC, bf16_t* VC, const float* __restrict__ qg, const float* __restrict__ kg, int gw, int NGW, int lane) {
;     ...
;         for (int k = 0; k < 3; ++k) {
;             float x[8];
; #pragma unroll
;             for (int e = 0; e < 4; ++e) { x[2 * e] = __uint_as_float(w[k][e] << 16); x[2 * e + 1] = __uint_as_float(w[k][e] & 0xffff0000u); }
;             float ss = 0.f;
; #pragma unroll
;             for (int e = 0; e < 8; ++e) ss += x[e] * x[e];
;             ss += pg8::xshfl(ss, 1, lane); ss += pg8::xshfl(ss, 2, lane); ss += pg8::xshfl(ss, 4, lane); ss += pg8::xshfl(ss, 8, lane);
;             const float rstd = 1.f / sqrtf(ss * (1.f / 128.f) + RMS_EPS);
;             const float* g = (k < 2 ? qg : kg) + 8 * q16;
;             float o[8];
; #pragma unroll
;             for (int e = 0; e < 8; ++e) { const float y = x[e] * rstd * g[e], yp = pg8::xshfl(y, 4, lane); const float ang = pos * invf[e], cs = __cosf(ang), sn = __sinf(ang);
;                 o[e] = first ? y * cs - yp * sn : y * cs + yp * sn; if (k < 2) o[e] *= (att::SCALE * 1.4426950408889634f); }
;             u32x4 r; r.x = pk2(o[0], o[1]); r.y = pk2(o[2], o[3]); r.z = pk2(o[4], o[5]); r.w = pk2(o[6], o[7]);
;             if (k < 2) src[lane + 64 * k] = r;
;             else if (lane < 32) *(u32x4*)(KC + ((size_t)(lane >> 4) * SEQ + t) * 128 + 8 * q16) = r;
;             else *(u32x4*)(VC + ((size_t)((lane - 32) >> 4) * SEQ + t) * 128 + 8 * q16) = w[2];
	v_mul_f32_e32 v51, v44, v51
	v_cndmask_b32_e64 v51, v51, -v51, s[42:43]
	v_fmac_f32_e32 v51, v42, v43
	v_mul_f32_e32 v43, v55, v45
	v_mul_f32_e32 v88, 0x3e0293ee, v51
	v_mul_f32_e32 v51, v49, v43
	v_mul_f32_e32 v43, v74, v46
	ds_bpermute_b32 v52, v80, v51
	v_mul_f32_e32 v45, 0.15915494, v43
	v_cos_f32_e32 v43, v45
	v_sin_f32_e32 v45, v45
	v_cvt_pk_bf16_f32 v87, v87, v88
	s_waitcnt lgkmcnt(0)
	v_mul_f32_e32 v52, v45, v52
	v_cndmask_b32_e64 v52, v52, -v52, s[42:43]
	v_fmac_f32_e32 v52, v43, v51
	v_mul_f32_e32 v51, v75, v46
	v_mul_f32_e32 v89, 0x3e0293ee, v52
	ds_bpermute_b32 v52, v80, v47
	v_mul_f32_e32 v53, 0.15915494, v51
	v_cos_f32_e32 v51, v53
	v_sin_f32_e32 v53, v53
	s_waitcnt lgkmcnt(0)
	v_mul_f32_e32 v52, v53, v52
	v_cndmask_b32_e64 v52, v52, -v52, s[42:43]
	v_fmac_f32_e32 v52, v51, v47
	v_mul_f32_e32 v47, v55, v50
	v_mul_f32_e32 v47, v61, v47
	v_mul_f32_e32 v50, v76, v46
	v_mul_f32_e32 v90, 0x3e0293ee, v52
	ds_bpermute_b32 v91, v80, v47
	v_mul_f32_e32 v52, 0.15915494, v50
	v_cos_f32_e32 v50, v52
	v_sin_f32_e32 v52, v52
	v_mul_f32_e32 v46, v77, v46
	v_cvt_pk_bf16_f32 v88, v89, v90
	s_waitcnt lgkmcnt(0)
	v_mul_f32_e32 v91, v52, v91
	v_cndmask_b32_e64 v91, v91, -v91, s[42:43]
	v_fmac_f32_e32 v91, v50, v47
	v_mul_f32_e32 v47, v55, v54
	v_mul_f32_e32 v54, v62, v47
	ds_bpermute_b32 v55, v80, v54
	v_mul_f32_e32 v47, 0.15915494, v46
	v_cos_f32_e32 v46, v47
	v_sin_f32_e32 v47, v47
	v_mul_f32_e32 v91, 0x3e0293ee, v91
	s_waitcnt lgkmcnt(0)
	v_mul_f32_e32 v55, v47, v55
	v_cndmask_b32_e64 v55, v55, -v55, s[42:43]
	v_fmac_f32_e32 v55, v46, v54
	v_mul_f32_e32 v54, 0x3e0293ee, v55
	v_cvt_pk_bf16_f32 v89, v91, v54
	v_lshlrev_b32_e32 v54, 16, v28
	v_and_b32_e32 v28, 0xffff0000, v28
	global_store_dwordx4 v82, v[86:89], s[12:13]
	v_lshlrev_b32_e32 v55, 16, v29
	v_and_b32_e32 v29, 0xffff0000, v29
	v_mul_f32_e32 v87, v28, v28
	v_fmac_f32_e32 v87, v54, v54
	v_fmac_f32_e32 v87, v55, v55
	v_fmac_f32_e32 v87, v29, v29
	v_fmac_f32_e32 v87, v85, v85
	v_lshlrev_b32_e32 v86, 16, v31
	v_fmac_f32_e32 v87, v30, v30
	v_and_b32_e32 v31, 0xffff0000, v31
	v_fmac_f32_e32 v87, v86, v86
	v_fmac_f32_e32 v87, v31, v31
	s_nop 1
	v_mov_b32_dpp v88, v87 quad_perm:[1,0,3,2] row_mask:0xf bank_mask:0xf
	s_waitcnt lgkmcnt(0)
	v_add_f32_e32 v87, v87, v88
	s_nop 1
	v_mov_b32_dpp v88, v87 quad_perm:[2,3,0,1] row_mask:0xf bank_mask:0xf
	s_waitcnt lgkmcnt(0)
	v_add_f32_e32 v87, v87, v88
	s_nop 1
	v_mov_b32_dpp v88, v87 row_half_mirror row_mask:0xf bank_mask:0xf
	s_waitcnt lgkmcnt(0)
	v_add_f32_e32 v87, v87, v88
	s_nop 1
	v_mov_b32_dpp v88, v87 row_mirror row_mask:0xf bank_mask:0xf
	s_waitcnt lgkmcnt(0)
	v_add_f32_e32 v87, v87, v88
	v_fmamk_f32 v87, v87, 0x3c000000, v231
	v_cmp_gt_f32_e32 vcc, s16, v87
	v_mul_f32_e32 v88, 0x4f800000, v87
	s_nop 0
	v_cndmask_b32_e32 v87, v87, v88, vcc
	v_sqrt_f32_e32 v88, v87
	s_nop 0
	v_add_u32_e32 v89, -1, v88
	v_fma_f32 v90, -v89, v88, v87
	v_cmp_ge_f32_e64 s[4:5], 0, v90
	v_add_u32_e32 v90, 1, v88
	s_nop 0
	v_cndmask_b32_e64 v89, v88, v89, s[4:5]
	v_fma_f32 v88, -v90, v88, v87
	v_cmp_lt_f32_e64 s[4:5], 0, v88
	s_nop 1
	v_cndmask_b32_e64 v88, v89, v90, s[4:5]
	v_mul_f32_e32 v89, 0x37800000, v88
	v_cndmask_b32_e32 v88, v88, v89, vcc
	v_cmp_class_f32_e32 vcc, v87, v233
	s_nop 1
	v_cndmask_b32_e32 v87, v88, v87, vcc
	v_div_scale_f32 v88, s[4:5], v87, v87, 1.0
	v_rcp_f32_e32 v89, v88
	s_nop 0
	v_fma_f32 v90, -v88, v89, 1.0
	v_fmac_f32_e32 v89, v90, v89
	v_div_scale_f32 v90, vcc, 1.0, v87, 1.0
	v_mul_f32_e32 v91, v90, v89
	v_fma_f32 v92, -v88, v91, v90
	v_fmac_f32_e32 v91, v92, v89
	v_fma_f32 v88, -v88, v91, v90
	v_div_fmas_f32 v88, v88, v89, v91
	v_div_fixup_f32 v87, v88, v87, 1.0
	v_mul_f32_e32 v54, v87, v54
	v_mul_f32_e32 v54, v56, v54
	ds_bpermute_b32 v88, v80, v54
	v_mul_f32_e32 v28, v87, v28
	v_mul_f32_e32 v28, v57, v28
	v_mul_f32_e32 v55, v87, v55
	v_mul_f32_e32 v55, v58, v55
	s_waitcnt lgkmcnt(0)
	v_mul_f32_e32 v88, v37, v88
	v_cndmask_b32_e64 v88, v88, -v88, s[42:43]
	v_fmac_f32_e32 v88, v36, v54
	v_mul_f32_e32 v54, 0x3e0293ee, v88
	ds_bpermute_b32 v88, v80, v28
	v_mul_f32_e32 v29, v87, v29
	v_mul_f32_e32 v29, v48, v29
	v_mul_f32_e32 v85, v87, v85
	v_mul_f32_e32 v85, v49, v85
	s_waitcnt lgkmcnt(0)
	v_mul_f32_e32 v88, v40, v88
	v_cndmask_b32_e64 v88, v88, -v88, s[42:43]
	v_fmac_f32_e32 v88, v38, v28
	v_mul_f32_e32 v28, 0x3e0293ee, v88
	ds_bpermute_b32 v88, v80, v55
	v_mul_f32_e32 v30, v87, v30
	v_mul_f32_e32 v30, v60, v30
	v_mul_f32_e32 v31, v87, v31
	v_mul_f32_e32 v86, v87, v86
	s_waitcnt lgkmcnt(0)
	v_mul_f32_e32 v88, v41, v88
	v_cndmask_b32_e64 v88, v88, -v88, s[42:43]
	v_fmac_f32_e32 v88, v39, v55
	v_mul_f32_e32 v55, 0x3e0293ee, v88
	ds_bpermute_b32 v88, v80, v29
	v_mul_f32_e32 v31, v62, v31
	v_mul_f32_e32 v86, v61, v86
	ds_bpermute_b32 v87, v80, v31
	v_cvt_pk_bf16_f32 v28, v54, v28
	s_waitcnt lgkmcnt(1)
	v_mul_f32_e32 v88, v44, v88
	v_cndmask_b32_e64 v88, v88, -v88, s[42:43]
	v_fmac_f32_e32 v88, v42, v29
	v_mul_f32_e32 v29, 0x3e0293ee, v88
	ds_bpermute_b32 v88, v80, v85
	s_waitcnt lgkmcnt(1)
	v_mul_f32_e32 v87, v47, v87
	v_cndmask_b32_e64 v87, v87, -v87, s[42:43]
	v_fmac_f32_e32 v87, v46, v31
	v_mul_f32_e32 v31, 0x3e0293ee, v87
	s_waitcnt lgkmcnt(0)
	v_mul_f32_e32 v88, v45, v88
	v_cndmask_b32_e64 v88, v88, -v88, s[42:43]
	v_fmac_f32_e32 v88, v43, v85
	v_mul_f32_e32 v85, 0x3e0293ee, v88
	ds_bpermute_b32 v88, v80, v30
	v_cvt_pk_bf16_f32 v29, v55, v29
	v_lshlrev_b32_e32 v54, 16, v22
	v_and_b32_e32 v55, 0xffff0000, v22
	s_waitcnt lgkmcnt(0)
	v_mul_f32_e32 v88, v53, v88
	v_cndmask_b32_e64 v88, v88, -v88, s[42:43]
	v_fmac_f32_e32 v88, v51, v30
	v_mul_f32_e32 v30, 0x3e0293ee, v88
	ds_bpermute_b32 v88, v80, v86
	v_cvt_pk_bf16_f32 v30, v85, v30
	v_lshlrev_b32_e32 v85, 16, v23
	s_waitcnt lgkmcnt(0)
; __device__ __forceinline__ float xshfl(float v, int o, int lane) { return __int_as_float(__builtin_amdgcn_ds_bpermute((lane ^ o) << 2, __float_as_int(v))); }
; __device__ __forceinline__ unsigned pk2(float lo, float hi) { unsigned r; asm volatile("v_cvt_pk_bf16_f32 %0, %1, %2" : "=v"(r) : "v"(lo), "v"(hi)); return r; }
; __device__ __forceinline__ void qk_prep(bf16_t* H, bf16_t* KC, bf16_t* VC, const float* __restrict__ qg, const float* __restrict__ kg, int gw, int NGW, int lane) {
;     ...
;         for (int k = 0; k < 3; ++k) {
;             float x[8];
; #pragma unroll
;             for (int e = 0; e < 4; ++e) { x[2 * e] = __uint_as_float(w[k][e] << 16); x[2 * e + 1] = __uint_as_float(w[k][e] & 0xffff0000u); }
;             float ss = 0.f;
; #pragma unroll
;             for (int e = 0; e < 8; ++e) ss += x[e] * x[e];
;             ss += pg8::xshfl(ss, 1, lane); ss += pg8::xshfl(ss, 2, lane); ss += pg8::xshfl(ss, 4, lane); ss += pg8::xshfl(ss, 8, lane);
;             const float rstd = 1.f / sqrtf(ss * (1.f / 128.f) + RMS_EPS);
;             const float* g = (k < 2 ? qg : kg) + 8 * q16;
;             float o[8];
; #pragma unroll
;             for (int e = 0; e < 8; ++e) { const float y = x[e] * rstd * g[e], yp = pg8::xshfl(y, 4, lane); const float ang = pos * invf[e], cs = __cosf(ang), sn = __sinf(ang);
;                 o[e] = first ? y * cs - yp * sn : y * cs + yp * sn; if (k < 2) o[e] *= (att::SCALE * 1.4426950408889634f); }
;             u32x4 r; r.x = pk2(o[0], o[1]); r.y = pk2(o[2], o[3]); r.z = pk2(o[4], o[5]); r.w = pk2(o[6], o[7]);
;             if (k < 2) src[lane + 64 * k] = r;
;             else if (lane < 32) *(u32x4*)(KC + ((size_t)(lane >> 4) * SEQ + t) * 128 + 8 * q16) = r;
;             else *(u32x4*)(VC + ((size_t)((lane - 32) >> 4) * SEQ + t) * 128 + 8 * q16) = w[2];
	v_mul_f32_e32 v88, v52, v88
	v_cndmask_b32_e64 v88, v88, -v88, s[42:43]
	v_fmac_f32_e32 v88, v50, v86
	v_mul_f32_e32 v86, 0x3e0293ee, v88
	v_cvt_pk_bf16_f32 v31, v86, v31
	global_store_dwordx4 v83, v[28:31], s[12:13]
	v_and_b32_e32 v86, 0xffff0000, v23
	s_nop 0
	v_and_b32_e32 v29, 0xffff0000, v20
	v_lshlrev_b32_e32 v28, 16, v20
	v_mul_f32_e32 v87, v29, v29
	v_lshlrev_b32_e32 v30, 16, v21
	v_fmac_f32_e32 v87, v28, v28
	v_and_b32_e32 v31, 0xffff0000, v21
	v_fmac_f32_e32 v87, v30, v30
	v_fmac_f32_e32 v87, v31, v31
	v_fmac_f32_e32 v87, v54, v54
	v_fmac_f32_e32 v87, v55, v55
	v_fmac_f32_e32 v87, v85, v85
	v_fmac_f32_e32 v87, v86, v86
	s_nop 1
	v_mov_b32_dpp v88, v87 quad_perm:[1,0,3,2] row_mask:0xf bank_mask:0xf
	s_waitcnt lgkmcnt(0)
	v_add_f32_e32 v87, v87, v88
	s_nop 1
	v_mov_b32_dpp v88, v87 quad_perm:[2,3,0,1] row_mask:0xf bank_mask:0xf
	s_waitcnt lgkmcnt(0)
	v_add_f32_e32 v87, v87, v88
	s_nop 1
	v_mov_b32_dpp v88, v87 row_half_mirror row_mask:0xf bank_mask:0xf
	s_waitcnt lgkmcnt(0)
	v_add_f32_e32 v87, v87, v88
	s_nop 1
	v_mov_b32_dpp v88, v87 row_mirror row_mask:0xf bank_mask:0xf
	s_waitcnt lgkmcnt(0)
	v_add_f32_e32 v87, v87, v88
	v_fmamk_f32 v87, v87, 0x3c000000, v231
	v_cmp_gt_f32_e32 vcc, s16, v87
	v_mul_f32_e32 v88, 0x4f800000, v87
	s_nop 0
	v_cndmask_b32_e32 v87, v87, v88, vcc
	v_sqrt_f32_e32 v88, v87
	s_nop 0
	v_add_u32_e32 v89, -1, v88
	v_fma_f32 v90, -v89, v88, v87
	v_cmp_ge_f32_e64 s[4:5], 0, v90
	v_add_u32_e32 v90, 1, v88
	s_nop 0
	v_cndmask_b32_e64 v89, v88, v89, s[4:5]
	v_fma_f32 v88, -v90, v88, v87
	v_cmp_lt_f32_e64 s[4:5], 0, v88
	s_nop 1
	v_cndmask_b32_e64 v88, v89, v90, s[4:5]
	v_mul_f32_e32 v89, 0x37800000, v88
	v_cndmask_b32_e32 v88, v88, v89, vcc
	v_cmp_class_f32_e32 vcc, v87, v233
	s_nop 1
	v_cndmask_b32_e32 v87, v88, v87, vcc
	v_div_scale_f32 v88, s[4:5], v87, v87, 1.0
	v_rcp_f32_e32 v89, v88
	s_ashr_i32 s4, s0, 6
	s_cmpk_lt_i32 s46, 0x2000
	v_fma_f32 v90, -v88, v89, 1.0
	v_fmac_f32_e32 v89, v90, v89
	v_div_scale_f32 v90, vcc, 1.0, v87, 1.0
	v_mul_f32_e32 v91, v90, v89
	v_fma_f32 v92, -v88, v91, v90
	v_fmac_f32_e32 v91, v92, v89
	v_fma_f32 v88, -v88, v91, v90
	v_div_fmas_f32 v88, v88, v89, v91
	v_div_fixup_f32 v87, v88, v87, 1.0
	v_mul_f32_e32 v28, v87, v28
	v_mul_f32_e32 v28, v32, v28
	ds_bpermute_b32 v88, v80, v28
	s_waitcnt lgkmcnt(0)
	v_mul_f32_e32 v37, v37, v88
	v_cndmask_b32_e64 v37, v37, -v37, s[42:43]
	v_fmac_f32_e32 v37, v36, v28
	v_mul_f32_e32 v28, v87, v29
	v_mul_f32_e32 v28, v33, v28
	ds_bpermute_b32 v29, v80, v28
	s_waitcnt lgkmcnt(0)
	v_mul_f32_e32 v29, v40, v29
	v_cndmask_b32_e64 v29, v29, -v29, s[42:43]
	v_fmac_f32_e32 v29, v38, v28
	v_mul_f32_e32 v28, v87, v30
	v_mul_f32_e32 v28, v34, v28
	ds_bpermute_b32 v30, v80, v28
	v_cvt_pk_bf16_f32 v37, v37, v29
	s_waitcnt lgkmcnt(0)
	v_mul_f32_e32 v30, v41, v30
	v_cndmask_b32_e64 v30, v30, -v30, s[42:43]
	v_fmac_f32_e32 v30, v39, v28
	v_mul_f32_e32 v28, v87, v31
	v_mul_f32_e32 v28, v35, v28
	ds_bpermute_b32 v31, v80, v28
	v_cndmask_b32_e64 v20, v20, v37, s[40:41]
	s_waitcnt lgkmcnt(0)
	v_mul_f32_e32 v31, v44, v31
	v_cndmask_b32_e64 v31, v31, -v31, s[42:43]
	v_fmac_f32_e32 v31, v42, v28
	v_mul_f32_e32 v28, v87, v54
	v_mul_f32_e32 v28, v24, v28
	ds_bpermute_b32 v36, v80, v28
	v_cvt_pk_bf16_f32 v30, v30, v31
	s_waitcnt lgkmcnt(0)
	v_mul_f32_e32 v36, v45, v36
	v_cndmask_b32_e64 v36, v36, -v36, s[42:43]
	v_fmac_f32_e32 v36, v43, v28
	v_mul_f32_e32 v28, v87, v55
	v_mul_f32_e32 v28, v25, v28
	ds_bpermute_b32 v38, v80, v28
	v_cndmask_b32_e64 v21, v21, v30, s[40:41]
	v_and_b32_e32 v30, 0xffff0000, v18
	s_waitcnt lgkmcnt(0)
	v_mul_f32_e32 v38, v53, v38
	v_cndmask_b32_e64 v38, v38, -v38, s[42:43]
	v_fmac_f32_e32 v38, v51, v28
	v_mul_f32_e32 v28, v87, v85
	v_mul_f32_e32 v28, v26, v28
	ds_bpermute_b32 v39, v80, v28
	v_cvt_pk_bf16_f32 v31, v36, v38
	s_waitcnt lgkmcnt(0)
	v_mul_f32_e32 v39, v52, v39
	v_cndmask_b32_e64 v39, v39, -v39, s[42:43]
	v_fmac_f32_e32 v39, v50, v28
	v_mul_f32_e32 v28, v87, v86
	v_mul_f32_e32 v28, v27, v28
	ds_bpermute_b32 v40, v80, v28
	v_cndmask_b32_e64 v22, v22, v31, s[40:41]
	v_lshlrev_b32_e32 v31, 16, v19
	s_waitcnt lgkmcnt(0)
	v_mul_f32_e32 v40, v47, v40
	v_cndmask_b32_e64 v40, v40, -v40, s[42:43]
	v_fmac_f32_e32 v40, v46, v28
	v_lshl_add_u64 v[28:29], v[112:113], 0, s[10:11]
	v_lshlrev_b64 v[28:29], 8, v[28:29]
	v_cvt_pk_bf16_f32 v36, v39, v40
	v_lshl_add_u64 v[28:29], v[68:69], 0, v[28:29]
	v_cndmask_b32_e64 v23, v23, v36, s[40:41]
	global_store_dwordx4 v[28:29], v[20:23], off
	v_lshlrev_b32_e32 v29, 16, v18
	v_and_b32_e32 v40, 0xffff0000, v19
	v_mov_b32_e32 v20, s1
	v_mov_b32_e32 v21, s4
	v_cndmask_b32_e64 v20, v20, v21, s[44:45]
	v_and_b32_e32 v21, 0xffff0000, v16
	v_cvt_f32_i32_e32 v28, v20
	v_lshlrev_b32_e32 v20, 16, v16
	v_mul_f32_e32 v16, v21, v21
	v_lshlrev_b32_e32 v22, 16, v17
	v_fmac_f32_e32 v16, v20, v20
	v_and_b32_e32 v23, 0xffff0000, v17
	v_fmac_f32_e32 v16, v22, v22
	v_fmac_f32_e32 v16, v23, v23
	v_fmac_f32_e32 v16, v29, v29
	v_fmac_f32_e32 v16, v30, v30
	v_fmac_f32_e32 v16, v31, v31
	v_fmac_f32_e32 v16, v40, v40
	s_nop 1
	v_mov_b32_dpp v17, v16 quad_perm:[1,0,3,2] row_mask:0xf bank_mask:0xf
	s_waitcnt lgkmcnt(0)
	v_add_f32_e32 v16, v16, v17
	s_nop 1
	v_mov_b32_dpp v17, v16 quad_perm:[2,3,0,1] row_mask:0xf bank_mask:0xf
	s_waitcnt lgkmcnt(0)
	v_add_f32_e32 v16, v16, v17
	s_nop 1
	v_mov_b32_dpp v17, v16 row_half_mirror row_mask:0xf bank_mask:0xf
	s_waitcnt lgkmcnt(0)
	v_add_f32_e32 v16, v16, v17
	s_nop 1
	v_mov_b32_dpp v17, v16 row_mirror row_mask:0xf bank_mask:0xf
	s_waitcnt lgkmcnt(0)
; __device__ __forceinline__ float xshfl(float v, int o, int lane) { return __int_as_float(__builtin_amdgcn_ds_bpermute((lane ^ o) << 2, __float_as_int(v))); }
; __device__ __forceinline__ unsigned pk2(float lo, float hi) { unsigned r; asm volatile("v_cvt_pk_bf16_f32 %0, %1, %2" : "=v"(r) : "v"(lo), "v"(hi)); return r; }
; __device__ __forceinline__ void qk_prep(bf16_t* H, bf16_t* KC, bf16_t* VC, const float* __restrict__ qg, const float* __restrict__ kg, int gw, int NGW, int lane) {
;     ...
;         for (int k = 0; k < 3; ++k) {
;             float x[8];
; #pragma unroll
;             for (int e = 0; e < 4; ++e) { x[2 * e] = __uint_as_float(w[k][e] << 16); x[2 * e + 1] = __uint_as_float(w[k][e] & 0xffff0000u); }
;             float ss = 0.f;
; #pragma unroll
;             for (int e = 0; e < 8; ++e) ss += x[e] * x[e];
;             ss += pg8::xshfl(ss, 1, lane); ss += pg8::xshfl(ss, 2, lane); ss += pg8::xshfl(ss, 4, lane); ss += pg8::xshfl(ss, 8, lane);
;             const float rstd = 1.f / sqrtf(ss * (1.f / 128.f) + RMS_EPS);
;             const float* g = (k < 2 ? qg : kg) + 8 * q16;
;             float o[8];
; #pragma unroll
;             for (int e = 0; e < 8; ++e) { const float y = x[e] * rstd * g[e], yp = pg8::xshfl(y, 4, lane); const float ang = pos * invf[e], cs = __cosf(ang), sn = __sinf(ang);
;                 o[e] = first ? y * cs - yp * sn : y * cs + yp * sn; if (k < 2) o[e] *= (att::SCALE * 1.4426950408889634f); }
;             u32x4 r; r.x = pk2(o[0], o[1]); r.y = pk2(o[2], o[3]); r.z = pk2(o[4], o[5]); r.w = pk2(o[6], o[7]);
;             if (k < 2) src[lane + 64 * k] = r;
;             else if (lane < 32) *(u32x4*)(KC + ((size_t)(lane >> 4) * SEQ + t) * 128 + 8 * q16) = r;
;             else *(u32x4*)(VC + ((size_t)((lane - 32) >> 4) * SEQ + t) * 128 + 8 * q16) = w[2];
	v_add_f32_e32 v16, v16, v17
	v_fmamk_f32 v16, v16, 0x3c000000, v231
	v_cmp_gt_f32_e32 vcc, s16, v16
	v_mul_f32_e32 v17, 0x4f800000, v16
	s_nop 0
	v_cndmask_b32_e32 v16, v16, v17, vcc
	v_sqrt_f32_e32 v17, v16
	s_nop 0
	v_add_u32_e32 v18, -1, v17
	v_fma_f32 v19, -v18, v17, v16
	v_cmp_ge_f32_e64 s[4:5], 0, v19
	v_add_u32_e32 v19, 1, v17
	s_nop 0
	v_cndmask_b32_e64 v18, v17, v18, s[4:5]
	v_fma_f32 v17, -v19, v17, v16
	v_cmp_lt_f32_e64 s[4:5], 0, v17
	s_nop 1
	v_cndmask_b32_e64 v17, v18, v19, s[4:5]
	v_mul_f32_e32 v18, 0x37800000, v17
	v_cndmask_b32_e32 v17, v17, v18, vcc
	v_cmp_class_f32_e32 vcc, v16, v233
	s_nop 1
	v_cndmask_b32_e32 v16, v17, v16, vcc
	v_div_scale_f32 v17, s[4:5], v16, v16, 1.0
	v_rcp_f32_e32 v18, v17
	s_nop 0
	v_fma_f32 v19, -v17, v18, 1.0
	v_fmac_f32_e32 v18, v19, v18
	v_div_scale_f32 v19, vcc, 1.0, v16, 1.0
	v_mul_f32_e32 v36, v19, v18
	v_fma_f32 v37, -v17, v36, v19
	v_fmac_f32_e32 v36, v37, v18
	v_fma_f32 v17, -v17, v36, v19
	v_div_fmas_f32 v17, v17, v18, v36
	v_div_fixup_f32 v41, v17, v16, 1.0
	v_mul_f32_e32 v16, v41, v20
	v_mul_f32_e32 v17, v56, v16
	v_mul_f32_e32 v16, v70, v28
	ds_bpermute_b32 v19, v80, v17
	v_mul_f32_e32 v18, 0.15915494, v16
	v_cos_f32_e32 v16, v18
	v_sin_f32_e32 v18, v18
	v_mul_f32_e32 v29, v41, v29
	v_mul_f32_e32 v30, v41, v30
	v_mul_f32_e32 v31, v41, v31
	s_waitcnt lgkmcnt(0)
	v_mul_f32_e32 v19, v18, v19
	v_cndmask_b32_e64 v19, v19, -v19, s[42:43]
	v_fmac_f32_e32 v19, v16, v17
	v_mul_f32_e32 v17, v41, v21
	v_mul_f32_e32 v20, v57, v17
	v_mul_f32_e32 v17, v71, v28
	v_mul_f32_e32 v42, 0x3e0293ee, v19
	ds_bpermute_b32 v21, v80, v20
	v_mul_f32_e32 v19, 0.15915494, v17
	v_cos_f32_e32 v17, v19
	v_sin_f32_e32 v19, v19
	v_mul_f32_e32 v31, v61, v31
	ds_bpermute_b32 v50, v80, v31
	s_waitcnt lgkmcnt(1)
	v_mul_f32_e32 v21, v19, v21
	v_cndmask_b32_e64 v21, v21, -v21, s[42:43]
	v_fmac_f32_e32 v21, v17, v20
	v_mul_f32_e32 v20, v41, v22
	v_mul_f32_e32 v43, 0x3e0293ee, v21
	v_mul_f32_e32 v21, v58, v20
	v_mul_f32_e32 v20, v72, v28
	ds_bpermute_b32 v36, v80, v21
	v_mul_f32_e32 v22, 0.15915494, v20
	v_cos_f32_e32 v20, v22
	v_sin_f32_e32 v22, v22
	s_waitcnt lgkmcnt(0)
	v_mul_f32_e32 v36, v22, v36
	v_cndmask_b32_e64 v36, v36, -v36, s[42:43]
	v_fmac_f32_e32 v36, v20, v21
	v_mul_f32_e32 v21, v41, v23
	v_mul_f32_e32 v44, 0x3e0293ee, v36
	v_mul_f32_e32 v36, v48, v21
	v_mul_f32_e32 v21, v73, v28
	ds_bpermute_b32 v37, v80, v36
	v_mul_f32_e32 v23, 0.15915494, v21
	v_cos_f32_e32 v21, v23
	v_sin_f32_e32 v23, v23
	s_waitcnt lgkmcnt(0)
	v_mul_f32_e32 v37, v23, v37
	v_cndmask_b32_e64 v37, v37, -v37, s[42:43]
	v_fmac_f32_e32 v37, v21, v36
	v_mul_f32_e32 v45, 0x3e0293ee, v37
	v_mul_f32_e32 v37, v49, v29
	v_mul_f32_e32 v29, v74, v28
	ds_bpermute_b32 v38, v80, v37
	v_mul_f32_e32 v36, 0.15915494, v29
	v_cos_f32_e32 v29, v36
	v_sin_f32_e32 v36, v36
	s_waitcnt lgkmcnt(0)
	v_mul_f32_e32 v38, v36, v38
	v_cndmask_b32_e64 v38, v38, -v38, s[42:43]
	v_fmac_f32_e32 v38, v29, v37
	v_mul_f32_e32 v46, 0x3e0293ee, v38
	v_mul_f32_e32 v38, v60, v30
	v_mul_f32_e32 v30, v75, v28
	ds_bpermute_b32 v39, v80, v38
	v_mul_f32_e32 v37, 0.15915494, v30
	v_cos_f32_e32 v30, v37
	v_sin_f32_e32 v37, v37
	s_waitcnt lgkmcnt(0)
	v_mul_f32_e32 v39, v37, v39
	v_cndmask_b32_e64 v39, v39, -v39, s[42:43]
	v_fmac_f32_e32 v39, v30, v38
	v_mul_f32_e32 v38, v76, v28
	v_mul_f32_e32 v47, 0x3e0293ee, v39
	v_mul_f32_e32 v39, 0.15915494, v38
	v_cos_f32_e32 v38, v39
	v_sin_f32_e32 v39, v39
	v_mul_f32_e32 v28, v77, v28
	v_mul_f32_e32 v50, v39, v50
	v_cndmask_b32_e64 v50, v50, -v50, s[42:43]
	v_fmac_f32_e32 v50, v38, v31
	v_mul_f32_e32 v31, v41, v40
	v_mul_f32_e32 v40, v62, v31
	ds_bpermute_b32 v41, v80, v40
	v_mul_f32_e32 v31, 0.15915494, v28
	v_cos_f32_e32 v28, v31
	v_sin_f32_e32 v31, v31
	v_mul_f32_e32 v50, 0x3e0293ee, v50
	s_waitcnt lgkmcnt(0)
	v_mul_f32_e32 v41, v31, v41
	v_cndmask_b32_e64 v41, v41, -v41, s[42:43]
	v_fmac_f32_e32 v41, v28, v40
	v_cvt_pk_bf16_f32 v40, v42, v43
	v_mul_f32_e32 v51, 0x3e0293ee, v41
	v_cvt_pk_bf16_f32 v41, v44, v45
	v_cvt_pk_bf16_f32 v42, v46, v47
	v_cvt_pk_bf16_f32 v43, v50, v51
	global_store_dwordx4 v82, v[40:43], s[8:9]
	s_nop 1
	v_lshlrev_b32_e32 v40, 16, v12
	v_and_b32_e32 v12, 0xffff0000, v12
	v_mul_f32_e32 v44, v12, v12
	v_lshlrev_b32_e32 v41, 16, v13
	v_fmac_f32_e32 v44, v40, v40
	v_and_b32_e32 v13, 0xffff0000, v13
	v_fmac_f32_e32 v44, v41, v41
	v_lshlrev_b32_e32 v42, 16, v14
	v_fmac_f32_e32 v44, v13, v13
	v_and_b32_e32 v14, 0xffff0000, v14
	v_fmac_f32_e32 v44, v42, v42
	v_lshlrev_b32_e32 v43, 16, v15
	v_fmac_f32_e32 v44, v14, v14
	v_and_b32_e32 v15, 0xffff0000, v15
	v_fmac_f32_e32 v44, v43, v43
	v_fmac_f32_e32 v44, v15, v15
	s_nop 1
	v_mov_b32_dpp v45, v44 quad_perm:[1,0,3,2] row_mask:0xf bank_mask:0xf
	s_waitcnt lgkmcnt(0)
	v_add_f32_e32 v44, v44, v45
	s_nop 1
	v_mov_b32_dpp v45, v44 quad_perm:[2,3,0,1] row_mask:0xf bank_mask:0xf
	s_waitcnt lgkmcnt(0)
	v_add_f32_e32 v44, v44, v45
	s_nop 1
	v_mov_b32_dpp v45, v44 row_half_mirror row_mask:0xf bank_mask:0xf
	s_waitcnt lgkmcnt(0)
	v_add_f32_e32 v44, v44, v45
	s_nop 1
	v_mov_b32_dpp v45, v44 row_mirror row_mask:0xf bank_mask:0xf
	s_waitcnt lgkmcnt(0)
; __device__ __forceinline__ float xshfl(float v, int o, int lane) { return __int_as_float(__builtin_amdgcn_ds_bpermute((lane ^ o) << 2, __float_as_int(v))); }
; __device__ __forceinline__ unsigned pk2(float lo, float hi) { unsigned r; asm volatile("v_cvt_pk_bf16_f32 %0, %1, %2" : "=v"(r) : "v"(lo), "v"(hi)); return r; }
; __device__ __forceinline__ void qk_prep(bf16_t* H, bf16_t* KC, bf16_t* VC, const float* __restrict__ qg, const float* __restrict__ kg, int gw, int NGW, int lane) {
;     ...
;         for (int k = 0; k < 3; ++k) {
;             float x[8];
; #pragma unroll
;             for (int e = 0; e < 4; ++e) { x[2 * e] = __uint_as_float(w[k][e] << 16); x[2 * e + 1] = __uint_as_float(w[k][e] & 0xffff0000u); }
;             float ss = 0.f;
; #pragma unroll
;             for (int e = 0; e < 8; ++e) ss += x[e] * x[e];
;             ss += pg8::xshfl(ss, 1, lane); ss += pg8::xshfl(ss, 2, lane); ss += pg8::xshfl(ss, 4, lane); ss += pg8::xshfl(ss, 8, lane);
;             const float rstd = 1.f / sqrtf(ss * (1.f / 128.f) + RMS_EPS);
;             const float* g = (k < 2 ? qg : kg) + 8 * q16;
;             float o[8];
; #pragma unroll
;             for (int e = 0; e < 8; ++e) { const float y = x[e] * rstd * g[e], yp = pg8::xshfl(y, 4, lane); const float ang = pos * invf[e], cs = __cosf(ang), sn = __sinf(ang);
;                 o[e] = first ? y * cs - yp * sn : y * cs + yp * sn; if (k < 2) o[e] *= (att::SCALE * 1.4426950408889634f); }
;             u32x4 r; r.x = pk2(o[0], o[1]); r.y = pk2(o[2], o[3]); r.z = pk2(o[4], o[5]); r.w = pk2(o[6], o[7]);
;             if (k < 2) src[lane + 64 * k] = r;
;             else if (lane < 32) *(u32x4*)(KC + ((size_t)(lane >> 4) * SEQ + t) * 128 + 8 * q16) = r;
;             else *(u32x4*)(VC + ((size_t)((lane - 32) >> 4) * SEQ + t) * 128 + 8 * q16) = w[2];
	v_add_f32_e32 v44, v44, v45
	v_fmamk_f32 v44, v44, 0x3c000000, v231
	v_cmp_gt_f32_e32 vcc, s16, v44
	v_mul_f32_e32 v45, 0x4f800000, v44
	s_nop 0
	v_cndmask_b32_e32 v44, v44, v45, vcc
	v_sqrt_f32_e32 v45, v44
	s_nop 0
	v_add_u32_e32 v46, -1, v45
	v_fma_f32 v47, -v46, v45, v44
	v_cmp_ge_f32_e64 s[4:5], 0, v47
	v_add_u32_e32 v47, 1, v45
	s_nop 0
	v_cndmask_b32_e64 v46, v45, v46, s[4:5]
	v_fma_f32 v45, -v47, v45, v44
	v_cmp_lt_f32_e64 s[4:5], 0, v45
	s_nop 1
	v_cndmask_b32_e64 v45, v46, v47, s[4:5]
	v_mul_f32_e32 v46, 0x37800000, v45
	v_cndmask_b32_e32 v45, v45, v46, vcc
	v_cmp_class_f32_e32 vcc, v44, v233
	s_nop 1
	v_cndmask_b32_e32 v44, v45, v44, vcc
	v_div_scale_f32 v45, s[4:5], v44, v44, 1.0
	v_rcp_f32_e32 v46, v45
	s_nop 0
	v_fma_f32 v47, -v45, v46, 1.0
	v_fmac_f32_e32 v46, v47, v46
	v_div_scale_f32 v47, vcc, 1.0, v44, 1.0
	v_mul_f32_e32 v50, v47, v46
	v_fma_f32 v51, -v45, v50, v47
	v_fmac_f32_e32 v50, v51, v46
	v_fma_f32 v45, -v45, v50, v47
	v_div_fmas_f32 v45, v45, v46, v50
	v_div_fixup_f32 v44, v45, v44, 1.0
	v_mul_f32_e32 v40, v44, v40
	v_mul_f32_e32 v40, v56, v40
	ds_bpermute_b32 v45, v80, v40
	v_mul_f32_e32 v12, v44, v12
	v_mul_f32_e32 v12, v57, v12
	v_mul_f32_e32 v41, v44, v41
	v_mul_f32_e32 v41, v58, v41
	s_waitcnt lgkmcnt(0)
	v_mul_f32_e32 v45, v18, v45
	v_cndmask_b32_e64 v45, v45, -v45, s[42:43]
	v_fmac_f32_e32 v45, v16, v40
	v_mul_f32_e32 v40, 0x3e0293ee, v45
	ds_bpermute_b32 v45, v80, v12
	v_mul_f32_e32 v13, v44, v13
	v_mul_f32_e32 v13, v48, v13
	v_mul_f32_e32 v42, v44, v42
	v_mul_f32_e32 v42, v49, v42
	s_waitcnt lgkmcnt(0)
	v_mul_f32_e32 v45, v19, v45
	v_cndmask_b32_e64 v45, v45, -v45, s[42:43]
	v_fmac_f32_e32 v45, v17, v12
	v_mul_f32_e32 v12, 0x3e0293ee, v45
	ds_bpermute_b32 v45, v80, v41
	v_mul_f32_e32 v14, v44, v14
	v_mul_f32_e32 v14, v60, v14
	v_mul_f32_e32 v15, v44, v15
	v_mul_f32_e32 v43, v44, v43
	s_waitcnt lgkmcnt(0)
	v_mul_f32_e32 v45, v22, v45
	v_cndmask_b32_e64 v45, v45, -v45, s[42:43]
	v_fmac_f32_e32 v45, v20, v41
	v_mul_f32_e32 v41, 0x3e0293ee, v45
	ds_bpermute_b32 v45, v80, v13
	v_mul_f32_e32 v15, v62, v15
	v_mul_f32_e32 v43, v61, v43
	ds_bpermute_b32 v44, v80, v15
	v_cvt_pk_bf16_f32 v12, v40, v12
	s_waitcnt lgkmcnt(1)
	v_mul_f32_e32 v45, v23, v45
	v_cndmask_b32_e64 v45, v45, -v45, s[42:43]
	v_fmac_f32_e32 v45, v21, v13
	v_mul_f32_e32 v13, 0x3e0293ee, v45
	ds_bpermute_b32 v45, v80, v42
	s_waitcnt lgkmcnt(1)
	v_mul_f32_e32 v44, v31, v44
	v_cndmask_b32_e64 v44, v44, -v44, s[42:43]
	v_fmac_f32_e32 v44, v28, v15
	v_mul_f32_e32 v15, 0x3e0293ee, v44
	s_waitcnt lgkmcnt(0)
	v_mul_f32_e32 v45, v36, v45
	v_cndmask_b32_e64 v45, v45, -v45, s[42:43]
	v_fmac_f32_e32 v45, v29, v42
	v_mul_f32_e32 v42, 0x3e0293ee, v45
	ds_bpermute_b32 v45, v80, v14
	v_cvt_pk_bf16_f32 v13, v41, v13
	v_lshlrev_b32_e32 v40, 16, v10
	v_and_b32_e32 v41, 0xffff0000, v10
	s_waitcnt lgkmcnt(0)
	v_mul_f32_e32 v45, v37, v45
	v_cndmask_b32_e64 v45, v45, -v45, s[42:43]
	v_fmac_f32_e32 v45, v30, v14
	v_mul_f32_e32 v14, 0x3e0293ee, v45
	ds_bpermute_b32 v45, v80, v43
	v_cvt_pk_bf16_f32 v14, v42, v14
	v_lshlrev_b32_e32 v42, 16, v11
	s_waitcnt lgkmcnt(0)
	v_mul_f32_e32 v45, v39, v45
	v_cndmask_b32_e64 v45, v45, -v45, s[42:43]
	v_fmac_f32_e32 v45, v38, v43
	v_mul_f32_e32 v43, 0x3e0293ee, v45
	v_cvt_pk_bf16_f32 v15, v43, v15
	global_store_dwordx4 v83, v[12:15], s[8:9]
	v_and_b32_e32 v43, 0xffff0000, v11
	s_nop 0
	v_and_b32_e32 v13, 0xffff0000, v8
	v_lshlrev_b32_e32 v12, 16, v8
	v_mul_f32_e32 v44, v13, v13
	v_lshlrev_b32_e32 v14, 16, v9
	v_fmac_f32_e32 v44, v12, v12
	v_and_b32_e32 v15, 0xffff0000, v9
	v_fmac_f32_e32 v44, v14, v14
	v_fmac_f32_e32 v44, v15, v15
	v_fmac_f32_e32 v44, v40, v40
	v_fmac_f32_e32 v44, v41, v41
	v_fmac_f32_e32 v44, v42, v42
	v_fmac_f32_e32 v44, v43, v43
	s_nop 1
	v_mov_b32_dpp v45, v44 quad_perm:[1,0,3,2] row_mask:0xf bank_mask:0xf
	s_waitcnt lgkmcnt(0)
; __device__ __forceinline__ float xshfl(float v, int o, int lane) { return __int_as_float(__builtin_amdgcn_ds_bpermute((lane ^ o) << 2, __float_as_int(v))); }
; __device__ __forceinline__ unsigned pk2(float lo, float hi) { unsigned r; asm volatile("v_cvt_pk_bf16_f32 %0, %1, %2" : "=v"(r) : "v"(lo), "v"(hi)); return r; }
; __device__ __forceinline__ void qk_prep(bf16_t* H, bf16_t* KC, bf16_t* VC, const float* __restrict__ qg, const float* __restrict__ kg, int gw, int NGW, int lane) {
;     ...
;         for (int k = 0; k < 3; ++k) {
;             float x[8];
; #pragma unroll
;             for (int e = 0; e < 4; ++e) { x[2 * e] = __uint_as_float(w[k][e] << 16); x[2 * e + 1] = __uint_as_float(w[k][e] & 0xffff0000u); }
;             float ss = 0.f;
; #pragma unroll
;             for (int e = 0; e < 8; ++e) ss += x[e] * x[e];
;             ss += pg8::xshfl(ss, 1, lane); ss += pg8::xshfl(ss, 2, lane); ss += pg8::xshfl(ss, 4, lane); ss += pg8::xshfl(ss, 8, lane);
;             const float rstd = 1.f / sqrtf(ss * (1.f / 128.f) + RMS_EPS);
;             const float* g = (k < 2 ? qg : kg) + 8 * q16;
;             float o[8];
; #pragma unroll
;             for (int e = 0; e < 8; ++e) { const float y = x[e] * rstd * g[e], yp = pg8::xshfl(y, 4, lane); const float ang = pos * invf[e], cs = __cosf(ang), sn = __sinf(ang);
;                 o[e] = first ? y * cs - yp * sn : y * cs + yp * sn; if (k < 2) o[e] *= (att::SCALE * 1.4426950408889634f); }
;             u32x4 r; r.x = pk2(o[0], o[1]); r.y = pk2(o[2], o[3]); r.z = pk2(o[4], o[5]); r.w = pk2(o[6], o[7]);
;             if (k < 2) src[lane + 64 * k] = r;
;             else if (lane < 32) *(u32x4*)(KC + ((size_t)(lane >> 4) * SEQ + t) * 128 + 8 * q16) = r;
;             else *(u32x4*)(VC + ((size_t)((lane - 32) >> 4) * SEQ + t) * 128 + 8 * q16) = w[2];
	v_add_f32_e32 v44, v44, v45
	s_nop 1
	v_mov_b32_dpp v45, v44 quad_perm:[2,3,0,1] row_mask:0xf bank_mask:0xf
	s_waitcnt lgkmcnt(0)
	v_add_f32_e32 v44, v44, v45
	s_nop 1
	v_mov_b32_dpp v45, v44 row_half_mirror row_mask:0xf bank_mask:0xf
	s_waitcnt lgkmcnt(0)
	v_add_f32_e32 v44, v44, v45
	s_nop 1
	v_mov_b32_dpp v45, v44 row_mirror row_mask:0xf bank_mask:0xf
	s_waitcnt lgkmcnt(0)
	v_add_f32_e32 v44, v44, v45
	v_fmamk_f32 v44, v44, 0x3c000000, v231
	v_cmp_gt_f32_e32 vcc, s16, v44
	v_mul_f32_e32 v45, 0x4f800000, v44
	s_nop 0
	v_cndmask_b32_e32 v44, v44, v45, vcc
	v_sqrt_f32_e32 v45, v44
	s_nop 0
	v_add_u32_e32 v46, -1, v45
	v_fma_f32 v47, -v46, v45, v44
	v_cmp_ge_f32_e64 s[4:5], 0, v47
	v_add_u32_e32 v47, 1, v45
	s_nop 0
	v_cndmask_b32_e64 v46, v45, v46, s[4:5]
	v_fma_f32 v45, -v47, v45, v44
	v_cmp_lt_f32_e64 s[4:5], 0, v45
	s_nop 1
	v_cndmask_b32_e64 v45, v46, v47, s[4:5]
	v_mul_f32_e32 v46, 0x37800000, v45
	v_cndmask_b32_e32 v45, v45, v46, vcc
	v_cmp_class_f32_e32 vcc, v44, v233
	s_nop 1
	v_cndmask_b32_e32 v44, v45, v44, vcc
	v_div_scale_f32 v45, s[4:5], v44, v44, 1.0
	v_rcp_f32_e32 v46, v45
	s_nop 0
	v_fma_f32 v47, -v45, v46, 1.0
	v_fmac_f32_e32 v46, v47, v46
	v_div_scale_f32 v47, vcc, 1.0, v44, 1.0
	v_mul_f32_e32 v48, v47, v46
	v_fma_f32 v49, -v45, v48, v47
	v_fmac_f32_e32 v48, v49, v46
	v_fma_f32 v45, -v45, v48, v47
	v_div_fmas_f32 v45, v45, v46, v48
	v_div_fixup_f32 v44, v45, v44, 1.0
	v_mul_f32_e32 v12, v44, v12
	v_mul_f32_e32 v12, v32, v12
	ds_bpermute_b32 v32, v80, v12
	s_waitcnt lgkmcnt(0)
	v_mul_f32_e32 v18, v18, v32
	v_cndmask_b32_e64 v18, v18, -v18, s[42:43]
	v_fmac_f32_e32 v18, v16, v12
	v_mul_f32_e32 v12, v44, v13
	v_mul_f32_e32 v12, v33, v12
	ds_bpermute_b32 v13, v80, v12
	s_waitcnt lgkmcnt(0)
	v_mul_f32_e32 v13, v19, v13
	v_cndmask_b32_e64 v13, v13, -v13, s[42:43]
	v_fmac_f32_e32 v13, v17, v12
	v_mul_f32_e32 v12, v44, v14
	v_mul_f32_e32 v12, v34, v12
	ds_bpermute_b32 v14, v80, v12
	v_cvt_pk_bf16_f32 v18, v18, v13
	s_waitcnt lgkmcnt(0)
	v_mul_f32_e32 v14, v22, v14
	v_cndmask_b32_e64 v14, v14, -v14, s[42:43]
	v_fmac_f32_e32 v14, v20, v12
	v_mul_f32_e32 v12, v44, v15
	v_mul_f32_e32 v12, v35, v12
	ds_bpermute_b32 v15, v80, v12
	v_cndmask_b32_e64 v8, v8, v18, s[40:41]
	s_waitcnt lgkmcnt(0)
	v_mul_f32_e32 v15, v23, v15
	v_cndmask_b32_e64 v15, v15, -v15, s[42:43]
	v_fmac_f32_e32 v15, v21, v12
	v_mul_f32_e32 v12, v44, v40
	v_mul_f32_e32 v12, v24, v12
	ds_bpermute_b32 v16, v80, v12
	v_cvt_pk_bf16_f32 v14, v14, v15
	s_waitcnt lgkmcnt(0)
	v_mul_f32_e32 v16, v36, v16
	v_cndmask_b32_e64 v16, v16, -v16, s[42:43]
	v_fmac_f32_e32 v16, v29, v12
	v_mul_f32_e32 v12, v44, v41
	v_mul_f32_e32 v12, v25, v12
	ds_bpermute_b32 v17, v80, v12
	v_cndmask_b32_e64 v9, v9, v14, s[40:41]
	s_waitcnt lgkmcnt(0)
	v_mul_f32_e32 v17, v37, v17
	v_cndmask_b32_e64 v17, v17, -v17, s[42:43]
	v_fmac_f32_e32 v17, v30, v12
	v_mul_f32_e32 v12, v44, v42
	v_mul_f32_e32 v12, v26, v12
	ds_bpermute_b32 v19, v80, v12
	v_cvt_pk_bf16_f32 v15, v16, v17
	s_waitcnt lgkmcnt(0)
	v_mul_f32_e32 v19, v39, v19
	v_cndmask_b32_e64 v19, v19, -v19, s[42:43]
	v_fmac_f32_e32 v19, v38, v12
	v_mul_f32_e32 v12, v44, v43
	v_mul_f32_e32 v12, v27, v12
	ds_bpermute_b32 v20, v80, v12
	v_cndmask_b32_e64 v10, v10, v15, s[40:41]
	s_waitcnt lgkmcnt(0)
	v_mul_f32_e32 v20, v31, v20
	v_cndmask_b32_e64 v20, v20, -v20, s[42:43]
	v_fmac_f32_e32 v20, v28, v12
	v_lshl_add_u64 v[12:13], v[112:113], 0, s[6:7]
	v_lshlrev_b64 v[12:13], 8, v[12:13]
	v_cvt_pk_bf16_f32 v16, v19, v20
	v_lshl_add_u64 v[12:13], v[68:69], 0, v[12:13]
	v_cndmask_b32_e64 v11, v11, v16, s[40:41]
	global_store_dwordx4 v[12:13], v[8:11], off
	s_cbranch_scc1 .LBB0_131
